# per-tile accumulator zeroing removed in 8 GEMM K-loops: first K-iteration peeled, first MFMA of each accumulator takes inline-zero srcC (bit-exact); plus SWA prologue single round trip
# speedup vs baseline: 1.0097x; 1.0013x over previous
.LBB0_199:
	s_ashr_i32 s31, s30, 31
	s_lshl_b64 s[46:47], s[30:31], 21
	s_add_u32 s46, s48, s46
	s_addc_u32 s47, s49, s47
	s_and_b64 s[50:51], s[4:5], exec
	s_cselect_b32 s2, s47, s61
	s_cselect_b32 s7, s46, s60
	s_ashr_i32 s25, s24, 31
	s_lshl_b64 s[50:51], s[24:25], 21
	s_add_u32 s50, s40, s50
	s_addc_u32 s51, s41, s51
	s_and_b64 s[62:63], s[4:5], exec
	s_cselect_b32 s25, s51, s55
	s_cselect_b32 s31, s50, s54
	s_add_u32 s60, s60, 0x100080
	s_addc_u32 s61, s61, 0
	s_add_u32 s59, s54, 0x100
	s_addc_u32 s69, s55, 0
	s_mov_b32 s70, -2
	ds_read_b128 v[166:169], v156
	ds_read_b128 v[170:173], v156 offset:1024
	ds_read_b128 v[174:177], v156 offset:2048
	ds_read_b128 v[178:181], v156 offset:3072
	ds_read_b128 v[182:185], v157
	ds_read_b128 v[186:189], v157 offset:1024
	ds_read_b128 v[190:193], v157 offset:2048
	ds_read_b128 v[194:197], v157 offset:3072
	s_add_u32 s54, s60, 0xfff00080
	s_addc_u32 s55, s61, -1
	s_cmp_eq_u32 s70, 60
	s_cselect_b32 s63, s2, s55
	s_cselect_b32 s62, s7, s54
	s_cselect_b32 s55, s25, s69
	s_cselect_b32 s54, s31, s59
	v_lshl_add_u64 v[160:161], s[60:61], 0, v[138:139]
	s_add_i32 m0, s26, 0xc000
	ds_read_b128 v[202:205], v158
	ds_read_b128 v[206:209], v158 offset:1024
	ds_read_b128 v[210:213], v158 offset:2048
	ds_read_b128 v[214:217], v158 offset:3072
	ds_read_b128 v[218:221], v158 offset:4096
	ds_read_b128 v[222:225], v158 offset:5120
	ds_read_b128 v[226:229], v158 offset:6144
	ds_read_b128 v[230:233], v158 offset:7168
	global_load_lds_dwordx4 v[160:161], off
	v_lshl_add_u64 v[160:161], s[60:61], 0, v[140:141]
	s_add_i32 m0, s26, 0xe000
	s_nop 0
	global_load_lds_dwordx4 v[160:161], off
	s_waitcnt vmcnt(8)
	s_waitcnt lgkmcnt(0)
	s_barrier
	s_setprio 1
	s_waitcnt lgkmcnt(0)
	v_mfma_f32_16x16x32_bf16 v[126:129], v[166:169], v[202:205], 0
	v_mfma_f32_16x16x32_bf16 v[122:125], v[174:177], v[202:205], 0
	v_mfma_f32_16x16x32_bf16 v[110:113], v[166:169], v[210:213], 0
	v_mfma_f32_16x16x32_bf16 v[106:109], v[174:177], v[210:213], 0
	v_mfma_f32_16x16x32_bf16 v[94:97], v[166:169], v[218:221], 0
	v_mfma_f32_16x16x32_bf16 v[90:93], v[174:177], v[218:221], 0
	v_mfma_f32_16x16x32_bf16 v[78:81], v[166:169], v[226:229], 0
	v_mfma_f32_16x16x32_bf16 v[74:77], v[174:177], v[226:229], 0
	v_mfma_f32_16x16x32_bf16 v[126:129], v[170:173], v[206:209], v[126:129]
	v_mfma_f32_16x16x32_bf16 v[122:125], v[178:181], v[206:209], v[122:125]
	v_mfma_f32_16x16x32_bf16 v[110:113], v[170:173], v[214:217], v[110:113]
	v_mfma_f32_16x16x32_bf16 v[106:109], v[178:181], v[214:217], v[106:109]
	v_mfma_f32_16x16x32_bf16 v[94:97], v[170:173], v[222:225], v[94:97]
	v_mfma_f32_16x16x32_bf16 v[90:93], v[178:181], v[222:225], v[90:93]
	v_mfma_f32_16x16x32_bf16 v[78:81], v[170:173], v[230:233], v[78:81]
	v_mfma_f32_16x16x32_bf16 v[74:77], v[178:181], v[230:233], v[74:77]
	s_setprio 0
	s_setprio 1
	v_mfma_f32_16x16x32_bf16 v[118:121], v[182:185], v[202:205], 0
	v_mfma_f32_16x16x32_bf16 v[114:117], v[190:193], v[202:205], 0
	v_mfma_f32_16x16x32_bf16 v[102:105], v[182:185], v[210:213], 0
	v_mfma_f32_16x16x32_bf16 v[98:101], v[190:193], v[210:213], 0
	v_mfma_f32_16x16x32_bf16 v[86:89], v[182:185], v[218:221], 0
	v_mfma_f32_16x16x32_bf16 v[82:85], v[190:193], v[218:221], 0
	v_mfma_f32_16x16x32_bf16 v[70:73], v[182:185], v[226:229], 0
	v_mfma_f32_16x16x32_bf16 v[66:69], v[190:193], v[226:229], 0
	v_mfma_f32_16x16x32_bf16 v[118:121], v[186:189], v[206:209], v[118:121]
	v_mfma_f32_16x16x32_bf16 v[114:117], v[194:197], v[206:209], v[114:117]
	v_mfma_f32_16x16x32_bf16 v[102:105], v[186:189], v[214:217], v[102:105]
	v_mfma_f32_16x16x32_bf16 v[98:101], v[194:197], v[214:217], v[98:101]
	v_mfma_f32_16x16x32_bf16 v[86:89], v[186:189], v[222:225], v[86:89]
	v_mfma_f32_16x16x32_bf16 v[82:85], v[194:197], v[222:225], v[82:85]
	v_mfma_f32_16x16x32_bf16 v[70:73], v[186:189], v[230:233], v[70:73]
	v_mfma_f32_16x16x32_bf16 v[66:69], v[194:197], v[230:233], v[66:69]
	s_setprio 0
	s_barrier
	s_add_i32 s71, s57, s21
	v_lshl_add_u64 v[160:161], s[54:55], 0, v[134:135]
	s_mov_b32 m0, s71
	ds_read_b128 v[202:205], v158 offset:16384
	ds_read_b128 v[206:209], v158 offset:17408
	ds_read_b128 v[210:213], v158 offset:18432
	ds_read_b128 v[214:217], v158 offset:19456
	ds_read_b128 v[218:221], v158 offset:20480
	ds_read_b128 v[222:225], v158 offset:21504
	ds_read_b128 v[226:229], v158 offset:22528
	ds_read_b128 v[230:233], v158 offset:23552
	global_load_lds_dwordx4 v[160:161], off
	s_add_i32 m0, s71, 0x2000
	s_add_u32 s72, s54, 0x100000
	v_lshl_add_u64 v[198:199], s[54:55], 0, v[136:137]
	s_addc_u32 s73, s55, 0
	s_add_i32 s71, s64, s21
	global_load_lds_dwordx4 v[198:199], off
	v_lshl_add_u64 v[234:235], s[72:73], 0, v[134:135]
	s_mov_b32 m0, s71
	v_lshl_add_u64 v[236:237], s[62:63], 0, v[132:133]
	global_load_lds_dwordx4 v[234:235], off
	v_lshl_add_u64 v[234:235], s[72:73], 0, v[136:137]
	s_add_i32 m0, s71, 0x2000
	s_nop 0
	global_load_lds_dwordx4 v[234:235], off
	v_lshl_add_u64 v[234:235], s[62:63], 0, v[130:131]
	s_mov_b32 m0, s26
	s_nop 0
	global_load_lds_dwordx4 v[234:235], off
	s_mov_b32 m0, s27
	s_nop 0
	global_load_lds_dwordx4 v[236:237], off
	s_waitcnt vmcnt(8)
	s_waitcnt lgkmcnt(0)
	s_barrier
	s_setprio 1
	s_waitcnt lgkmcnt(0)
	v_mfma_f32_16x16x32_bf16 v[62:65], v[166:169], v[202:205], 0
	v_mfma_f32_16x16x32_bf16 v[58:61], v[174:177], v[202:205], 0
	v_mfma_f32_16x16x32_bf16 v[46:49], v[166:169], v[210:213], 0
	v_mfma_f32_16x16x32_bf16 v[42:45], v[174:177], v[210:213], 0
	v_mfma_f32_16x16x32_bf16 v[30:33], v[166:169], v[218:221], 0
	v_mfma_f32_16x16x32_bf16 v[26:29], v[174:177], v[218:221], 0
	v_mfma_f32_16x16x32_bf16 v[14:17], v[166:169], v[226:229], 0
	v_mfma_f32_16x16x32_bf16 v[10:13], v[174:177], v[226:229], 0
	v_mfma_f32_16x16x32_bf16 v[62:65], v[170:173], v[206:209], v[62:65]
	v_mfma_f32_16x16x32_bf16 v[58:61], v[178:181], v[206:209], v[58:61]
	v_mfma_f32_16x16x32_bf16 v[46:49], v[170:173], v[214:217], v[46:49]
	v_mfma_f32_16x16x32_bf16 v[42:45], v[178:181], v[214:217], v[42:45]
	v_mfma_f32_16x16x32_bf16 v[30:33], v[170:173], v[222:225], v[30:33]
	v_mfma_f32_16x16x32_bf16 v[26:29], v[178:181], v[222:225], v[26:29]
	v_mfma_f32_16x16x32_bf16 v[14:17], v[170:173], v[230:233], v[14:17]
	v_mfma_f32_16x16x32_bf16 v[10:13], v[178:181], v[230:233], v[10:13]
	s_setprio 0
	s_setprio 1
	v_mfma_f32_16x16x32_bf16 v[54:57], v[182:185], v[202:205], 0
	v_mfma_f32_16x16x32_bf16 v[50:53], v[190:193], v[202:205], 0
	v_mfma_f32_16x16x32_bf16 v[38:41], v[182:185], v[210:213], 0
	v_mfma_f32_16x16x32_bf16 v[34:37], v[190:193], v[210:213], 0
	v_mfma_f32_16x16x32_bf16 v[22:25], v[182:185], v[218:221], 0
	v_mfma_f32_16x16x32_bf16 v[18:21], v[190:193], v[218:221], 0
	v_mfma_f32_16x16x32_bf16 v[6:9], v[182:185], v[226:229], 0
	v_mfma_f32_16x16x32_bf16 v[2:5], v[190:193], v[226:229], 0
	v_mfma_f32_16x16x32_bf16 v[54:57], v[186:189], v[206:209], v[54:57]
	v_mfma_f32_16x16x32_bf16 v[50:53], v[194:197], v[206:209], v[50:53]
	v_mfma_f32_16x16x32_bf16 v[38:41], v[186:189], v[214:217], v[38:41]
	v_mfma_f32_16x16x32_bf16 v[34:37], v[194:197], v[214:217], v[34:37]
	v_mfma_f32_16x16x32_bf16 v[22:25], v[186:189], v[222:225], v[22:25]
	v_mfma_f32_16x16x32_bf16 v[18:21], v[194:197], v[222:225], v[18:21]
	v_mfma_f32_16x16x32_bf16 v[6:9], v[186:189], v[230:233], v[6:9]
	v_mfma_f32_16x16x32_bf16 v[2:5], v[194:197], v[230:233], v[2:5]
	s_setprio 0
	s_barrier
	s_add_i32 s71, 0, 0x18000
	v_add_u32_e32 v163, s71, v154
	s_add_i32 s72, 0, 0x1c000
	ds_read_b128 v[166:169], v163
	ds_read_b128 v[170:173], v163 offset:1024
	ds_read_b128 v[174:177], v163 offset:2048
	ds_read_b128 v[178:181], v163 offset:3072
	v_add_u32_e32 v163, s72, v154
	ds_read_b128 v[182:185], v163
	ds_read_b128 v[186:189], v163 offset:1024
	ds_read_b128 v[190:193], v163 offset:2048
	ds_read_b128 v[194:197], v163 offset:3072
	s_add_u32 s62, s62, 0x100000
	s_addc_u32 s63, s63, 0
	s_mov_b32 m0, s36
	v_lshl_add_u64 v[238:239], s[62:63], 0, v[130:131]
	ds_read_b128 v[202:205], v158 offset:32768
	ds_read_b128 v[206:209], v158 offset:33792
	ds_read_b128 v[210:213], v158 offset:34816
	ds_read_b128 v[214:217], v158 offset:35840
	ds_read_b128 v[218:221], v158 offset:36864
	ds_read_b128 v[222:225], v158 offset:37888
	ds_read_b128 v[226:229], v158 offset:38912
	ds_read_b128 v[230:233], v158 offset:39936
	global_load_lds_dwordx4 v[238:239], off
	v_lshl_add_u64 v[238:239], s[62:63], 0, v[132:133]
	s_mov_b32 m0, s37
	s_nop 0
	global_load_lds_dwordx4 v[238:239], off
	s_waitcnt vmcnt(8)
	s_waitcnt lgkmcnt(0)
	s_barrier
	s_setprio 1
	s_waitcnt lgkmcnt(0)
	v_mfma_f32_16x16x32_bf16 v[126:129], v[166:169], v[202:205], v[126:129]
	v_mfma_f32_16x16x32_bf16 v[122:125], v[174:177], v[202:205], v[122:125]
	v_mfma_f32_16x16x32_bf16 v[110:113], v[166:169], v[210:213], v[110:113]
	v_mfma_f32_16x16x32_bf16 v[106:109], v[174:177], v[210:213], v[106:109]
	v_mfma_f32_16x16x32_bf16 v[94:97], v[166:169], v[218:221], v[94:97]
	v_mfma_f32_16x16x32_bf16 v[90:93], v[174:177], v[218:221], v[90:93]
	v_mfma_f32_16x16x32_bf16 v[78:81], v[166:169], v[226:229], v[78:81]
	v_mfma_f32_16x16x32_bf16 v[74:77], v[174:177], v[226:229], v[74:77]
	v_mfma_f32_16x16x32_bf16 v[126:129], v[170:173], v[206:209], v[126:129]
	v_mfma_f32_16x16x32_bf16 v[122:125], v[178:181], v[206:209], v[122:125]
	v_mfma_f32_16x16x32_bf16 v[110:113], v[170:173], v[214:217], v[110:113]
	v_mfma_f32_16x16x32_bf16 v[106:109], v[178:181], v[214:217], v[106:109]
	v_mfma_f32_16x16x32_bf16 v[94:97], v[170:173], v[222:225], v[94:97]
	v_mfma_f32_16x16x32_bf16 v[90:93], v[178:181], v[222:225], v[90:93]
	v_mfma_f32_16x16x32_bf16 v[78:81], v[170:173], v[230:233], v[78:81]
	v_mfma_f32_16x16x32_bf16 v[74:77], v[178:181], v[230:233], v[74:77]
	s_setprio 0
	s_setprio 1
	v_mfma_f32_16x16x32_bf16 v[118:121], v[182:185], v[202:205], v[118:121]
	v_mfma_f32_16x16x32_bf16 v[114:117], v[190:193], v[202:205], v[114:117]
	v_mfma_f32_16x16x32_bf16 v[102:105], v[182:185], v[210:213], v[102:105]
	v_mfma_f32_16x16x32_bf16 v[98:101], v[190:193], v[210:213], v[98:101]
	v_mfma_f32_16x16x32_bf16 v[86:89], v[182:185], v[218:221], v[86:89]
	v_mfma_f32_16x16x32_bf16 v[82:85], v[190:193], v[218:221], v[82:85]
	v_mfma_f32_16x16x32_bf16 v[70:73], v[182:185], v[226:229], v[70:73]
	v_mfma_f32_16x16x32_bf16 v[66:69], v[190:193], v[226:229], v[66:69]
	v_mfma_f32_16x16x32_bf16 v[118:121], v[186:189], v[206:209], v[118:121]
	v_mfma_f32_16x16x32_bf16 v[114:117], v[194:197], v[206:209], v[114:117]
	v_mfma_f32_16x16x32_bf16 v[102:105], v[186:189], v[214:217], v[102:105]
	v_mfma_f32_16x16x32_bf16 v[98:101], v[194:197], v[214:217], v[98:101]
	v_mfma_f32_16x16x32_bf16 v[86:89], v[186:189], v[222:225], v[86:89]
	v_mfma_f32_16x16x32_bf16 v[82:85], v[194:197], v[222:225], v[82:85]
	v_mfma_f32_16x16x32_bf16 v[70:73], v[186:189], v[230:233], v[70:73]
	v_mfma_f32_16x16x32_bf16 v[66:69], v[194:197], v[230:233], v[66:69]
	s_setprio 0
	s_barrier
	s_add_i32 s62, s71, s21
	v_lshl_add_u64 v[160:161], v[160:161], 0, s[14:15]
	s_mov_b32 m0, s62
	ds_read_b128 v[202:205], v158 offset:49152
	ds_read_b128 v[206:209], v158 offset:50176
	ds_read_b128 v[210:213], v158 offset:51200
	ds_read_b128 v[214:217], v158 offset:52224
	ds_read_b128 v[218:221], v158 offset:53248
	ds_read_b128 v[222:225], v158 offset:54272
	ds_read_b128 v[226:229], v158 offset:55296
	ds_read_b128 v[230:233], v158 offset:56320
	global_load_lds_dwordx4 v[160:161], off
	s_add_i32 m0, s62, 0x2000
	s_add_u32 s54, s54, 0x100080
	v_lshl_add_u64 v[160:161], v[198:199], 0, s[14:15]
	s_addc_u32 s55, s55, 0
	s_add_i32 s62, s72, s21
	global_load_lds_dwordx4 v[160:161], off
	v_lshl_add_u64 v[160:161], s[54:55], 0, v[134:135]
	s_mov_b32 m0, s62
	s_nop 0
	global_load_lds_dwordx4 v[160:161], off
	v_lshl_add_u64 v[160:161], s[54:55], 0, v[136:137]
	s_add_i32 m0, s62, 0x2000
	s_nop 0
	global_load_lds_dwordx4 v[160:161], off
	v_lshl_add_u64 v[160:161], v[234:235], 0, s[14:15]
	s_mov_b32 m0, s52
	s_nop 0
	global_load_lds_dwordx4 v[160:161], off
	v_lshl_add_u64 v[160:161], v[236:237], 0, s[14:15]
	s_mov_b32 m0, s53
	s_nop 0
	global_load_lds_dwordx4 v[160:161], off
	s_waitcnt vmcnt(8)
	s_waitcnt lgkmcnt(0)
	s_barrier
	s_setprio 1
	s_waitcnt lgkmcnt(0)
	v_mfma_f32_16x16x32_bf16 v[62:65], v[166:169], v[202:205], v[62:65]
	v_mfma_f32_16x16x32_bf16 v[58:61], v[174:177], v[202:205], v[58:61]
	v_mfma_f32_16x16x32_bf16 v[46:49], v[166:169], v[210:213], v[46:49]
	v_mfma_f32_16x16x32_bf16 v[42:45], v[174:177], v[210:213], v[42:45]
	v_mfma_f32_16x16x32_bf16 v[30:33], v[166:169], v[218:221], v[30:33]
	v_mfma_f32_16x16x32_bf16 v[26:29], v[174:177], v[218:221], v[26:29]
	v_mfma_f32_16x16x32_bf16 v[14:17], v[166:169], v[226:229], v[14:17]
	v_mfma_f32_16x16x32_bf16 v[10:13], v[174:177], v[226:229], v[10:13]
	v_mfma_f32_16x16x32_bf16 v[62:65], v[170:173], v[206:209], v[62:65]
	v_mfma_f32_16x16x32_bf16 v[58:61], v[178:181], v[206:209], v[58:61]
	v_mfma_f32_16x16x32_bf16 v[46:49], v[170:173], v[214:217], v[46:49]
	v_mfma_f32_16x16x32_bf16 v[42:45], v[178:181], v[214:217], v[42:45]
	v_mfma_f32_16x16x32_bf16 v[30:33], v[170:173], v[222:225], v[30:33]
	v_mfma_f32_16x16x32_bf16 v[26:29], v[178:181], v[222:225], v[26:29]
	v_mfma_f32_16x16x32_bf16 v[14:17], v[170:173], v[230:233], v[14:17]
	v_mfma_f32_16x16x32_bf16 v[10:13], v[178:181], v[230:233], v[10:13]
	s_setprio 0
	s_setprio 1
	v_mfma_f32_16x16x32_bf16 v[54:57], v[182:185], v[202:205], v[54:57]
	v_mfma_f32_16x16x32_bf16 v[50:53], v[190:193], v[202:205], v[50:53]
	v_mfma_f32_16x16x32_bf16 v[38:41], v[182:185], v[210:213], v[38:41]
	v_mfma_f32_16x16x32_bf16 v[34:37], v[190:193], v[210:213], v[34:37]
	v_mfma_f32_16x16x32_bf16 v[22:25], v[182:185], v[218:221], v[22:25]
	v_mfma_f32_16x16x32_bf16 v[18:21], v[190:193], v[218:221], v[18:21]
	v_mfma_f32_16x16x32_bf16 v[6:9], v[182:185], v[226:229], v[6:9]
	v_mfma_f32_16x16x32_bf16 v[2:5], v[190:193], v[226:229], v[2:5]
	v_mfma_f32_16x16x32_bf16 v[54:57], v[186:189], v[206:209], v[54:57]
	v_mfma_f32_16x16x32_bf16 v[50:53], v[194:197], v[206:209], v[50:53]
	v_mfma_f32_16x16x32_bf16 v[38:41], v[186:189], v[214:217], v[38:41]
	v_mfma_f32_16x16x32_bf16 v[34:37], v[194:197], v[214:217], v[34:37]
	v_mfma_f32_16x16x32_bf16 v[22:25], v[186:189], v[222:225], v[22:25]
	v_mfma_f32_16x16x32_bf16 v[18:21], v[194:197], v[222:225], v[18:21]
	v_mfma_f32_16x16x32_bf16 v[6:9], v[186:189], v[230:233], v[6:9]
	v_mfma_f32_16x16x32_bf16 v[2:5], v[194:197], v[230:233], v[2:5]
	s_setprio 0
	s_barrier
	s_add_i32 s70, s70, 2
	s_add_u32 s60, s60, 0x100
	s_addc_u32 s61, s61, 0
	s_add_u32 s59, s59, 0x100
	s_addc_u32 s69, s69, 0

.LBB0_247:
	s_ashr_i32 s47, s46, 31
	s_lshl_b64 s[58:59], s[46:47], 21
	s_add_u32 s58, s20, s58
	s_addc_u32 s59, s21, s59
	s_and_b64 s[62:63], s[60:61], exec
	s_cselect_b32 s15, s59, s65
	s_cselect_b32 s47, s58, s64
	s_ashr_i32 s51, s50, 31
	s_lshl_b64 s[62:63], s[50:51], 21
	v_readlane_b32 s66, v250, 11
	v_readlane_b32 s67, v250, 12
	s_add_u32 s62, s66, s62
	s_addc_u32 s63, s67, s63
	s_and_b64 s[66:67], s[60:61], exec
	s_cselect_b32 s51, s63, s55
	s_cselect_b32 s68, s62, s54
	s_add_u32 s64, s64, 0x100080
	s_addc_u32 s65, s65, 0
	s_add_u32 s69, s54, 0x100
	s_addc_u32 s70, s55, 0
	s_mov_b32 s71, -2
	ds_read_b128 v[144:147], v140
	ds_read_b128 v[148:151], v140 offset:1024
	ds_read_b128 v[152:155], v140 offset:2048
	ds_read_b128 v[156:159], v140 offset:3072
	ds_read_b128 v[166:169], v141
	ds_read_b128 v[170:173], v141 offset:1024
	ds_read_b128 v[174:177], v141 offset:2048
	ds_read_b128 v[178:181], v141 offset:3072
	s_add_u32 s54, s64, 0xfff00080
	s_addc_u32 s55, s65, -1
	s_cmp_eq_u32 s71, 60
	s_cselect_b32 s67, s15, s55
	s_cselect_b32 s66, s47, s54
	s_cselect_b32 s55, s51, s70
	s_cselect_b32 s54, s68, s69
	v_lshl_add_u64 v[160:161], s[64:65], 0, v[134:135]
	s_add_i32 m0, s23, 0xc000
	ds_read_b128 v[182:185], v142
	ds_read_b128 v[186:189], v142 offset:1024
	ds_read_b128 v[190:193], v142 offset:2048
	ds_read_b128 v[194:197], v142 offset:3072
	ds_read_b128 v[202:205], v142 offset:4096
	ds_read_b128 v[206:209], v142 offset:5120
	ds_read_b128 v[210:213], v142 offset:6144
	ds_read_b128 v[214:217], v142 offset:7168
	global_load_lds_dwordx4 v[160:161], off
	v_lshl_add_u64 v[160:161], s[64:65], 0, v[136:137]
	s_add_i32 m0, s23, 0xe000
	s_nop 0
	global_load_lds_dwordx4 v[160:161], off
	s_waitcnt vmcnt(8)
	s_waitcnt lgkmcnt(0)
	s_barrier
	s_setprio 1
	s_waitcnt lgkmcnt(0)
	v_mfma_f32_16x16x32_bf16 v[126:129], v[144:147], v[182:185], 0
	v_mfma_f32_16x16x32_bf16 v[122:125], v[152:155], v[182:185], 0
	v_mfma_f32_16x16x32_bf16 v[118:121], v[144:147], v[190:193], 0
	v_mfma_f32_16x16x32_bf16 v[114:117], v[152:155], v[190:193], 0
	v_mfma_f32_16x16x32_bf16 v[110:113], v[144:147], v[202:205], 0
	v_mfma_f32_16x16x32_bf16 v[102:105], v[152:155], v[202:205], 0
	v_mfma_f32_16x16x32_bf16 v[94:97], v[144:147], v[210:213], 0
	v_mfma_f32_16x16x32_bf16 v[86:89], v[152:155], v[210:213], 0
	v_mfma_f32_16x16x32_bf16 v[126:129], v[148:151], v[186:189], v[126:129]
	v_mfma_f32_16x16x32_bf16 v[122:125], v[156:159], v[186:189], v[122:125]
	v_mfma_f32_16x16x32_bf16 v[118:121], v[148:151], v[194:197], v[118:121]
	v_mfma_f32_16x16x32_bf16 v[114:117], v[156:159], v[194:197], v[114:117]
	v_mfma_f32_16x16x32_bf16 v[110:113], v[148:151], v[206:209], v[110:113]
	v_mfma_f32_16x16x32_bf16 v[102:105], v[156:159], v[206:209], v[102:105]
	v_mfma_f32_16x16x32_bf16 v[94:97], v[148:151], v[214:217], v[94:97]
	v_mfma_f32_16x16x32_bf16 v[86:89], v[156:159], v[214:217], v[86:89]
	s_setprio 0
	s_setprio 1
	v_mfma_f32_16x16x32_bf16 v[106:109], v[166:169], v[182:185], 0
	v_mfma_f32_16x16x32_bf16 v[98:101], v[174:177], v[182:185], 0
	v_mfma_f32_16x16x32_bf16 v[90:93], v[166:169], v[190:193], 0
	v_mfma_f32_16x16x32_bf16 v[82:85], v[174:177], v[190:193], 0
	v_mfma_f32_16x16x32_bf16 v[78:81], v[166:169], v[202:205], 0
	v_mfma_f32_16x16x32_bf16 v[74:77], v[174:177], v[202:205], 0
	v_mfma_f32_16x16x32_bf16 v[70:73], v[166:169], v[210:213], 0
	v_mfma_f32_16x16x32_bf16 v[66:69], v[174:177], v[210:213], 0
	v_mfma_f32_16x16x32_bf16 v[106:109], v[170:173], v[186:189], v[106:109]
	v_mfma_f32_16x16x32_bf16 v[98:101], v[178:181], v[186:189], v[98:101]
	v_mfma_f32_16x16x32_bf16 v[90:93], v[170:173], v[194:197], v[90:93]
	v_mfma_f32_16x16x32_bf16 v[82:85], v[178:181], v[194:197], v[82:85]
	v_mfma_f32_16x16x32_bf16 v[78:81], v[170:173], v[206:209], v[78:81]
	v_mfma_f32_16x16x32_bf16 v[74:77], v[178:181], v[206:209], v[74:77]
	v_mfma_f32_16x16x32_bf16 v[70:73], v[170:173], v[214:217], v[70:73]
	v_mfma_f32_16x16x32_bf16 v[66:69], v[178:181], v[214:217], v[66:69]
	s_setprio 0
	s_barrier
	s_add_i32 s72, s56, s4
	v_lshl_add_u64 v[160:161], s[54:55], 0, v[130:131]
	s_mov_b32 m0, s72
	ds_read_b128 v[182:185], v142 offset:16384
	ds_read_b128 v[186:189], v142 offset:17408
	ds_read_b128 v[190:193], v142 offset:18432
	ds_read_b128 v[194:197], v142 offset:19456
	ds_read_b128 v[202:205], v142 offset:20480
	ds_read_b128 v[206:209], v142 offset:21504
	ds_read_b128 v[210:213], v142 offset:22528
	ds_read_b128 v[214:217], v142 offset:23552
	global_load_lds_dwordx4 v[160:161], off
	s_add_i32 m0, s72, 0x2000
	s_add_u32 s72, s54, 0x100000
	v_lshl_add_u64 v[198:199], s[54:55], 0, v[132:133]
	s_addc_u32 s73, s55, 0
	s_add_i32 s74, s57, s4
	global_load_lds_dwordx4 v[198:199], off
	v_lshl_add_u64 v[218:219], s[72:73], 0, v[130:131]
	s_mov_b32 m0, s74
	v_lshl_add_u64 v[220:221], s[66:67], 0, v[132:133]
	global_load_lds_dwordx4 v[218:219], off
	v_lshl_add_u64 v[218:219], s[72:73], 0, v[132:133]
	s_add_i32 m0, s74, 0x2000
	s_nop 0
	global_load_lds_dwordx4 v[218:219], off
	v_lshl_add_u64 v[218:219], s[66:67], 0, v[130:131]
	s_mov_b32 m0, s23
	s_nop 0
	global_load_lds_dwordx4 v[218:219], off
	s_mov_b32 m0, s27
	s_nop 0
	global_load_lds_dwordx4 v[220:221], off
	s_waitcnt vmcnt(8)
	s_waitcnt lgkmcnt(0)
	s_barrier
	s_setprio 1
	s_waitcnt lgkmcnt(0)
	v_mfma_f32_16x16x32_bf16 v[62:65], v[144:147], v[182:185], 0
	v_mfma_f32_16x16x32_bf16 v[58:61], v[152:155], v[182:185], 0
	v_mfma_f32_16x16x32_bf16 v[54:57], v[144:147], v[190:193], 0
	v_mfma_f32_16x16x32_bf16 v[50:53], v[152:155], v[190:193], 0
	v_mfma_f32_16x16x32_bf16 v[46:49], v[144:147], v[202:205], 0
	v_mfma_f32_16x16x32_bf16 v[38:41], v[152:155], v[202:205], 0
	v_mfma_f32_16x16x32_bf16 v[30:33], v[144:147], v[210:213], 0
	v_mfma_f32_16x16x32_bf16 v[22:25], v[152:155], v[210:213], 0
	v_mfma_f32_16x16x32_bf16 v[62:65], v[148:151], v[186:189], v[62:65]
	v_mfma_f32_16x16x32_bf16 v[58:61], v[156:159], v[186:189], v[58:61]
	v_mfma_f32_16x16x32_bf16 v[54:57], v[148:151], v[194:197], v[54:57]
	v_mfma_f32_16x16x32_bf16 v[50:53], v[156:159], v[194:197], v[50:53]
	v_mfma_f32_16x16x32_bf16 v[46:49], v[148:151], v[206:209], v[46:49]
	v_mfma_f32_16x16x32_bf16 v[38:41], v[156:159], v[206:209], v[38:41]
	v_mfma_f32_16x16x32_bf16 v[30:33], v[148:151], v[214:217], v[30:33]
	v_mfma_f32_16x16x32_bf16 v[22:25], v[156:159], v[214:217], v[22:25]
	s_setprio 0
	s_setprio 1
	v_mfma_f32_16x16x32_bf16 v[42:45], v[166:169], v[182:185], 0
	v_mfma_f32_16x16x32_bf16 v[34:37], v[174:177], v[182:185], 0
	v_mfma_f32_16x16x32_bf16 v[26:29], v[166:169], v[190:193], 0
	v_mfma_f32_16x16x32_bf16 v[18:21], v[174:177], v[190:193], 0
	v_mfma_f32_16x16x32_bf16 v[14:17], v[166:169], v[202:205], 0
	v_mfma_f32_16x16x32_bf16 v[10:13], v[174:177], v[202:205], 0
	v_mfma_f32_16x16x32_bf16 v[6:9], v[166:169], v[210:213], 0
	v_mfma_f32_16x16x32_bf16 v[2:5], v[174:177], v[210:213], 0
	v_mfma_f32_16x16x32_bf16 v[42:45], v[170:173], v[186:189], v[42:45]
	v_mfma_f32_16x16x32_bf16 v[34:37], v[178:181], v[186:189], v[34:37]
	v_mfma_f32_16x16x32_bf16 v[26:29], v[170:173], v[194:197], v[26:29]
	v_mfma_f32_16x16x32_bf16 v[18:21], v[178:181], v[194:197], v[18:21]
	v_mfma_f32_16x16x32_bf16 v[14:17], v[170:173], v[206:209], v[14:17]
	v_mfma_f32_16x16x32_bf16 v[10:13], v[178:181], v[206:209], v[10:13]
	v_mfma_f32_16x16x32_bf16 v[6:9], v[170:173], v[214:217], v[6:9]
	v_mfma_f32_16x16x32_bf16 v[2:5], v[178:181], v[214:217], v[2:5]
	s_setprio 0
	s_barrier
	s_add_i32 s72, 0, 0x18000
	s_add_i32 s73, 0, 0x1c000
	v_add_u32_e32 v156, s72, v138
	v_add_u32_e32 v163, s73, v138
	ds_read_b128 v[144:147], v156
	ds_read_b128 v[148:151], v156 offset:1024
	ds_read_b128 v[152:155], v156 offset:2048
	ds_read_b128 v[156:159], v156 offset:3072
	ds_read_b128 v[166:169], v163
	ds_read_b128 v[170:173], v163 offset:1024
	ds_read_b128 v[174:177], v163 offset:2048
	ds_read_b128 v[178:181], v163 offset:3072
	s_add_u32 s66, s66, 0x100000
	s_addc_u32 s67, s67, 0
	s_mov_b32 m0, s36
	v_lshl_add_u64 v[222:223], s[66:67], 0, v[130:131]
	ds_read_b128 v[182:185], v142 offset:32768
	ds_read_b128 v[186:189], v142 offset:33792
	ds_read_b128 v[190:193], v142 offset:34816
	ds_read_b128 v[194:197], v142 offset:35840
	ds_read_b128 v[202:205], v142 offset:36864
	ds_read_b128 v[206:209], v142 offset:37888
	ds_read_b128 v[210:213], v142 offset:38912
	ds_read_b128 v[214:217], v142 offset:39936
	global_load_lds_dwordx4 v[222:223], off
	v_lshl_add_u64 v[222:223], s[66:67], 0, v[132:133]
	s_mov_b32 m0, s37
	s_nop 0
	global_load_lds_dwordx4 v[222:223], off
	s_waitcnt vmcnt(8)
	s_waitcnt lgkmcnt(0)
	s_barrier
	s_setprio 1
	s_waitcnt lgkmcnt(0)
	v_mfma_f32_16x16x32_bf16 v[126:129], v[144:147], v[182:185], v[126:129]
	v_mfma_f32_16x16x32_bf16 v[122:125], v[152:155], v[182:185], v[122:125]
	v_mfma_f32_16x16x32_bf16 v[118:121], v[144:147], v[190:193], v[118:121]
	v_mfma_f32_16x16x32_bf16 v[114:117], v[152:155], v[190:193], v[114:117]
	v_mfma_f32_16x16x32_bf16 v[110:113], v[144:147], v[202:205], v[110:113]
	v_mfma_f32_16x16x32_bf16 v[102:105], v[152:155], v[202:205], v[102:105]
	v_mfma_f32_16x16x32_bf16 v[94:97], v[144:147], v[210:213], v[94:97]
	v_mfma_f32_16x16x32_bf16 v[86:89], v[152:155], v[210:213], v[86:89]
	v_mfma_f32_16x16x32_bf16 v[126:129], v[148:151], v[186:189], v[126:129]
	v_mfma_f32_16x16x32_bf16 v[122:125], v[156:159], v[186:189], v[122:125]
	v_mfma_f32_16x16x32_bf16 v[118:121], v[148:151], v[194:197], v[118:121]
	v_mfma_f32_16x16x32_bf16 v[114:117], v[156:159], v[194:197], v[114:117]
	v_mfma_f32_16x16x32_bf16 v[110:113], v[148:151], v[206:209], v[110:113]
	v_mfma_f32_16x16x32_bf16 v[102:105], v[156:159], v[206:209], v[102:105]
	v_mfma_f32_16x16x32_bf16 v[94:97], v[148:151], v[214:217], v[94:97]
	v_mfma_f32_16x16x32_bf16 v[86:89], v[156:159], v[214:217], v[86:89]
	s_setprio 0
	s_setprio 1
	v_mfma_f32_16x16x32_bf16 v[106:109], v[166:169], v[182:185], v[106:109]
	v_mfma_f32_16x16x32_bf16 v[98:101], v[174:177], v[182:185], v[98:101]
	v_mfma_f32_16x16x32_bf16 v[90:93], v[166:169], v[190:193], v[90:93]
	v_mfma_f32_16x16x32_bf16 v[82:85], v[174:177], v[190:193], v[82:85]
	v_mfma_f32_16x16x32_bf16 v[78:81], v[166:169], v[202:205], v[78:81]
	v_mfma_f32_16x16x32_bf16 v[74:77], v[174:177], v[202:205], v[74:77]
	v_mfma_f32_16x16x32_bf16 v[70:73], v[166:169], v[210:213], v[70:73]
	v_mfma_f32_16x16x32_bf16 v[66:69], v[174:177], v[210:213], v[66:69]
	v_mfma_f32_16x16x32_bf16 v[106:109], v[170:173], v[186:189], v[106:109]
	v_mfma_f32_16x16x32_bf16 v[98:101], v[178:181], v[186:189], v[98:101]
	v_mfma_f32_16x16x32_bf16 v[90:93], v[170:173], v[194:197], v[90:93]
	v_mfma_f32_16x16x32_bf16 v[82:85], v[178:181], v[194:197], v[82:85]
	v_mfma_f32_16x16x32_bf16 v[78:81], v[170:173], v[206:209], v[78:81]
	v_mfma_f32_16x16x32_bf16 v[74:77], v[178:181], v[206:209], v[74:77]
	v_mfma_f32_16x16x32_bf16 v[70:73], v[170:173], v[214:217], v[70:73]
	v_mfma_f32_16x16x32_bf16 v[66:69], v[178:181], v[214:217], v[66:69]
	s_setprio 0
	s_barrier
	s_add_i32 s66, s72, s4
	v_lshl_add_u64 v[160:161], v[160:161], 0, s[24:25]
	s_mov_b32 m0, s66
	ds_read_b128 v[182:185], v142 offset:49152
	ds_read_b128 v[186:189], v142 offset:50176
	ds_read_b128 v[190:193], v142 offset:51200
	ds_read_b128 v[194:197], v142 offset:52224
	ds_read_b128 v[202:205], v142 offset:53248
	ds_read_b128 v[206:209], v142 offset:54272
	ds_read_b128 v[210:213], v142 offset:55296
	ds_read_b128 v[214:217], v142 offset:56320
	global_load_lds_dwordx4 v[160:161], off
	s_add_i32 m0, s66, 0x2000
	s_add_u32 s54, s54, 0x100080
	v_lshl_add_u64 v[160:161], v[198:199], 0, s[24:25]
	s_addc_u32 s55, s55, 0
	s_add_i32 s66, s73, s4
	global_load_lds_dwordx4 v[160:161], off
	v_lshl_add_u64 v[160:161], s[54:55], 0, v[130:131]
	s_mov_b32 m0, s66
	s_nop 0
	global_load_lds_dwordx4 v[160:161], off
	v_lshl_add_u64 v[160:161], s[54:55], 0, v[132:133]
	s_add_i32 m0, s66, 0x2000
	s_nop 0
	global_load_lds_dwordx4 v[160:161], off
	v_lshl_add_u64 v[160:161], v[218:219], 0, s[24:25]
	s_mov_b32 m0, s39
	s_nop 0
	global_load_lds_dwordx4 v[160:161], off
	v_lshl_add_u64 v[160:161], v[220:221], 0, s[24:25]
	s_mov_b32 m0, s52
	s_nop 0
	global_load_lds_dwordx4 v[160:161], off
	s_waitcnt vmcnt(8)
	s_waitcnt lgkmcnt(0)
	s_barrier
	s_setprio 1
	s_waitcnt lgkmcnt(0)
	v_mfma_f32_16x16x32_bf16 v[62:65], v[144:147], v[182:185], v[62:65]
	v_mfma_f32_16x16x32_bf16 v[58:61], v[152:155], v[182:185], v[58:61]
	v_mfma_f32_16x16x32_bf16 v[54:57], v[144:147], v[190:193], v[54:57]
	v_mfma_f32_16x16x32_bf16 v[50:53], v[152:155], v[190:193], v[50:53]
	v_mfma_f32_16x16x32_bf16 v[46:49], v[144:147], v[202:205], v[46:49]
	v_mfma_f32_16x16x32_bf16 v[38:41], v[152:155], v[202:205], v[38:41]
	v_mfma_f32_16x16x32_bf16 v[30:33], v[144:147], v[210:213], v[30:33]
	v_mfma_f32_16x16x32_bf16 v[22:25], v[152:155], v[210:213], v[22:25]
	v_mfma_f32_16x16x32_bf16 v[62:65], v[148:151], v[186:189], v[62:65]
	v_mfma_f32_16x16x32_bf16 v[58:61], v[156:159], v[186:189], v[58:61]
	v_mfma_f32_16x16x32_bf16 v[54:57], v[148:151], v[194:197], v[54:57]
	v_mfma_f32_16x16x32_bf16 v[50:53], v[156:159], v[194:197], v[50:53]
	v_mfma_f32_16x16x32_bf16 v[46:49], v[148:151], v[206:209], v[46:49]
	v_mfma_f32_16x16x32_bf16 v[38:41], v[156:159], v[206:209], v[38:41]
	v_mfma_f32_16x16x32_bf16 v[30:33], v[148:151], v[214:217], v[30:33]
	v_mfma_f32_16x16x32_bf16 v[22:25], v[156:159], v[214:217], v[22:25]
	s_setprio 0
	s_setprio 1
	v_mfma_f32_16x16x32_bf16 v[42:45], v[166:169], v[182:185], v[42:45]
	v_mfma_f32_16x16x32_bf16 v[34:37], v[174:177], v[182:185], v[34:37]
	v_mfma_f32_16x16x32_bf16 v[26:29], v[166:169], v[190:193], v[26:29]
	v_mfma_f32_16x16x32_bf16 v[18:21], v[174:177], v[190:193], v[18:21]
	v_mfma_f32_16x16x32_bf16 v[14:17], v[166:169], v[202:205], v[14:17]
	v_mfma_f32_16x16x32_bf16 v[10:13], v[174:177], v[202:205], v[10:13]
	v_mfma_f32_16x16x32_bf16 v[6:9], v[166:169], v[210:213], v[6:9]
	v_mfma_f32_16x16x32_bf16 v[2:5], v[174:177], v[210:213], v[2:5]
	v_mfma_f32_16x16x32_bf16 v[42:45], v[170:173], v[186:189], v[42:45]
	v_mfma_f32_16x16x32_bf16 v[34:37], v[178:181], v[186:189], v[34:37]
	v_mfma_f32_16x16x32_bf16 v[26:29], v[170:173], v[194:197], v[26:29]
	v_mfma_f32_16x16x32_bf16 v[18:21], v[178:181], v[194:197], v[18:21]
	v_mfma_f32_16x16x32_bf16 v[14:17], v[170:173], v[206:209], v[14:17]
	v_mfma_f32_16x16x32_bf16 v[10:13], v[178:181], v[206:209], v[10:13]
	v_mfma_f32_16x16x32_bf16 v[6:9], v[170:173], v[214:217], v[6:9]
	v_mfma_f32_16x16x32_bf16 v[2:5], v[178:181], v[214:217], v[2:5]
	s_setprio 0
	s_barrier
	s_add_i32 s71, s71, 2
	s_add_u32 s64, s64, 0x100
	s_addc_u32 s65, s65, 0
	s_add_u32 s69, s69, 0x100
	s_addc_u32 s70, s70, 0

.LBB0_829:
	s_add_u32 s30, s30, 0x38080
	s_addc_u32 s31, s31, 0
	s_add_u32 s73, s54, 0x100
	s_addc_u32 s74, s55, 0
	s_mov_b32 s75, -2
	ds_read_b128 v[170:173], v167
	ds_read_b128 v[174:177], v167 offset:1024
	ds_read_b128 v[178:181], v167 offset:2048
	ds_read_b128 v[182:185], v167 offset:3072
	ds_read_b128 v[186:189], v168
	ds_read_b128 v[190:193], v168 offset:1024
	ds_read_b128 v[194:197], v168 offset:2048
	ds_read_b128 v[202:205], v168 offset:3072
	s_add_u32 s54, s30, 0xfffc8080
	s_addc_u32 s55, s31, -1
	s_cmp_eq_u32 s75, 10
	s_cselect_b32 s67, s7, s55
	s_cselect_b32 s66, s6, s54
	s_cselect_b32 s55, s25, s74
	s_cselect_b32 s54, s24, s73
	v_lshl_add_u64 v[146:147], s[30:31], 0, v[138:139]
	s_add_i32 m0, s26, 0xc000
	ds_read_b128 v[206:209], v169
	ds_read_b128 v[210:213], v169 offset:1024
	ds_read_b128 v[214:217], v169 offset:2048
	ds_read_b128 v[218:221], v169 offset:3072
	ds_read_b128 v[222:225], v169 offset:4096
	ds_read_b128 v[226:229], v169 offset:5120
	ds_read_b128 v[230:233], v169 offset:6144
	ds_read_b128 v[234:237], v169 offset:7168
	global_load_lds_dwordx4 v[146:147], off
	v_lshl_add_u64 v[146:147], s[30:31], 0, v[140:141]
	s_add_i32 m0, s26, 0xe000
	s_nop 0
	global_load_lds_dwordx4 v[146:147], off
	s_waitcnt vmcnt(8)
	s_waitcnt lgkmcnt(0)
	s_barrier
	s_setprio 1
	s_waitcnt lgkmcnt(0)
	v_mfma_f32_16x16x32_bf16 v[126:129], v[170:173], v[206:209], 0
	v_mfma_f32_16x16x32_bf16 v[122:125], v[178:181], v[206:209], 0
	v_mfma_f32_16x16x32_bf16 v[110:113], v[170:173], v[214:217], 0
	v_mfma_f32_16x16x32_bf16 v[106:109], v[178:181], v[214:217], 0
	v_mfma_f32_16x16x32_bf16 v[102:105], v[170:173], v[222:225], 0
	v_mfma_f32_16x16x32_bf16 v[98:101], v[178:181], v[222:225], 0
	v_mfma_f32_16x16x32_bf16 v[86:89], v[170:173], v[230:233], 0
	v_mfma_f32_16x16x32_bf16 v[82:85], v[178:181], v[230:233], 0
	v_mfma_f32_16x16x32_bf16 v[126:129], v[174:177], v[210:213], v[126:129]
	v_mfma_f32_16x16x32_bf16 v[122:125], v[182:185], v[210:213], v[122:125]
	v_mfma_f32_16x16x32_bf16 v[110:113], v[174:177], v[218:221], v[110:113]
	v_mfma_f32_16x16x32_bf16 v[106:109], v[182:185], v[218:221], v[106:109]
	v_mfma_f32_16x16x32_bf16 v[102:105], v[174:177], v[226:229], v[102:105]
	v_mfma_f32_16x16x32_bf16 v[98:101], v[182:185], v[226:229], v[98:101]
	v_mfma_f32_16x16x32_bf16 v[86:89], v[174:177], v[234:237], v[86:89]
	v_mfma_f32_16x16x32_bf16 v[82:85], v[182:185], v[234:237], v[82:85]
	s_setprio 0
	s_setprio 1
	v_mfma_f32_16x16x32_bf16 v[118:121], v[186:189], v[206:209], 0
	v_mfma_f32_16x16x32_bf16 v[114:117], v[194:197], v[206:209], 0
	v_mfma_f32_16x16x32_bf16 v[94:97], v[186:189], v[214:217], 0
	v_mfma_f32_16x16x32_bf16 v[90:93], v[194:197], v[214:217], 0
	v_mfma_f32_16x16x32_bf16 v[78:81], v[186:189], v[222:225], 0
	v_mfma_f32_16x16x32_bf16 v[74:77], v[194:197], v[222:225], 0
	v_mfma_f32_16x16x32_bf16 v[70:73], v[186:189], v[230:233], 0
	v_mfma_f32_16x16x32_bf16 v[66:69], v[194:197], v[230:233], 0
	v_mfma_f32_16x16x32_bf16 v[118:121], v[190:193], v[210:213], v[118:121]
	v_mfma_f32_16x16x32_bf16 v[114:117], v[202:205], v[210:213], v[114:117]
	v_mfma_f32_16x16x32_bf16 v[94:97], v[190:193], v[218:221], v[94:97]
	v_mfma_f32_16x16x32_bf16 v[90:93], v[202:205], v[218:221], v[90:93]
	v_mfma_f32_16x16x32_bf16 v[78:81], v[190:193], v[226:229], v[78:81]
	v_mfma_f32_16x16x32_bf16 v[74:77], v[202:205], v[226:229], v[74:77]
	v_mfma_f32_16x16x32_bf16 v[70:73], v[190:193], v[234:237], v[70:73]
	v_mfma_f32_16x16x32_bf16 v[66:69], v[202:205], v[234:237], v[66:69]
	s_setprio 0
	s_barrier
	s_add_i32 s76, s56, s21
	v_lshl_add_u64 v[146:147], s[54:55], 0, v[134:135]
	s_mov_b32 m0, s76
	ds_read_b128 v[206:209], v169 offset:16384
	ds_read_b128 v[210:213], v169 offset:17408
	ds_read_b128 v[214:217], v169 offset:18432
	ds_read_b128 v[218:221], v169 offset:19456
	ds_read_b128 v[222:225], v169 offset:20480
	ds_read_b128 v[226:229], v169 offset:21504
	ds_read_b128 v[230:233], v169 offset:22528
	ds_read_b128 v[234:237], v169 offset:23552
	global_load_lds_dwordx4 v[146:147], off
	s_add_i32 m0, s76, 0x2000
	s_add_u32 s76, s54, 0x38000
	v_lshl_add_u64 v[198:199], s[54:55], 0, v[130:131]
	s_addc_u32 s77, s55, 0
	s_add_i32 s78, s57, s21
	global_load_lds_dwordx4 v[198:199], off
	v_lshl_add_u64 v[238:239], s[76:77], 0, v[134:135]
	s_mov_b32 m0, s78
	v_lshl_add_u64 v[240:241], s[66:67], 0, v[132:133]
	global_load_lds_dwordx4 v[238:239], off
	v_lshl_add_u64 v[238:239], s[76:77], 0, v[130:131]
	s_add_i32 m0, s78, 0x2000
	s_nop 0
	global_load_lds_dwordx4 v[238:239], off
	v_lshl_add_u64 v[238:239], s[66:67], 0, v[136:137]
	s_mov_b32 m0, s26
	s_nop 0
	global_load_lds_dwordx4 v[238:239], off
	s_mov_b32 m0, s27
	s_nop 0
	global_load_lds_dwordx4 v[240:241], off
	s_waitcnt vmcnt(8)
	s_waitcnt lgkmcnt(0)
	s_barrier
	s_setprio 1
	s_waitcnt lgkmcnt(0)
	v_mfma_f32_16x16x32_bf16 v[62:65], v[170:173], v[206:209], 0
	v_mfma_f32_16x16x32_bf16 v[58:61], v[178:181], v[206:209], 0
	v_mfma_f32_16x16x32_bf16 v[54:57], v[170:173], v[214:217], 0
	v_mfma_f32_16x16x32_bf16 v[50:53], v[178:181], v[214:217], 0
	v_mfma_f32_16x16x32_bf16 v[38:41], v[170:173], v[222:225], 0
	v_mfma_f32_16x16x32_bf16 v[34:37], v[178:181], v[222:225], 0
	v_mfma_f32_16x16x32_bf16 v[22:25], v[170:173], v[230:233], 0
	v_mfma_f32_16x16x32_bf16 v[18:21], v[178:181], v[230:233], 0
	v_mfma_f32_16x16x32_bf16 v[62:65], v[174:177], v[210:213], v[62:65]
	v_mfma_f32_16x16x32_bf16 v[58:61], v[182:185], v[210:213], v[58:61]
	v_mfma_f32_16x16x32_bf16 v[54:57], v[174:177], v[218:221], v[54:57]
	v_mfma_f32_16x16x32_bf16 v[50:53], v[182:185], v[218:221], v[50:53]
	v_mfma_f32_16x16x32_bf16 v[38:41], v[174:177], v[226:229], v[38:41]
	v_mfma_f32_16x16x32_bf16 v[34:37], v[182:185], v[226:229], v[34:37]
	v_mfma_f32_16x16x32_bf16 v[22:25], v[174:177], v[234:237], v[22:25]
	v_mfma_f32_16x16x32_bf16 v[18:21], v[182:185], v[234:237], v[18:21]
	s_setprio 0
	s_setprio 1
	v_mfma_f32_16x16x32_bf16 v[46:49], v[186:189], v[206:209], 0
	v_mfma_f32_16x16x32_bf16 v[42:45], v[194:197], v[206:209], 0
	v_mfma_f32_16x16x32_bf16 v[30:33], v[186:189], v[214:217], 0
	v_mfma_f32_16x16x32_bf16 v[26:29], v[194:197], v[214:217], 0
	v_mfma_f32_16x16x32_bf16 v[14:17], v[186:189], v[222:225], 0
	v_mfma_f32_16x16x32_bf16 v[10:13], v[194:197], v[222:225], 0
	v_mfma_f32_16x16x32_bf16 v[6:9], v[186:189], v[230:233], 0
	v_mfma_f32_16x16x32_bf16 v[2:5], v[194:197], v[230:233], 0
	v_mfma_f32_16x16x32_bf16 v[46:49], v[190:193], v[210:213], v[46:49]
	v_mfma_f32_16x16x32_bf16 v[42:45], v[202:205], v[210:213], v[42:45]
	v_mfma_f32_16x16x32_bf16 v[30:33], v[190:193], v[218:221], v[30:33]
	v_mfma_f32_16x16x32_bf16 v[26:29], v[202:205], v[218:221], v[26:29]
	v_mfma_f32_16x16x32_bf16 v[14:17], v[190:193], v[226:229], v[14:17]
	v_mfma_f32_16x16x32_bf16 v[10:13], v[202:205], v[226:229], v[10:13]
	v_mfma_f32_16x16x32_bf16 v[6:9], v[190:193], v[234:237], v[6:9]
	v_mfma_f32_16x16x32_bf16 v[2:5], v[202:205], v[234:237], v[2:5]
	s_setprio 0
	s_barrier
	s_add_i32 s76, 0, 0x18000
	s_add_i32 s77, 0, 0x1c000
	v_add_u32_e32 v182, s76, v163
	v_add_u32_e32 v201, s77, v163
	ds_read_b128 v[170:173], v182
	ds_read_b128 v[174:177], v182 offset:1024
	ds_read_b128 v[178:181], v182 offset:2048
	ds_read_b128 v[182:185], v182 offset:3072
	ds_read_b128 v[186:189], v201
	ds_read_b128 v[190:193], v201 offset:1024
	ds_read_b128 v[194:197], v201 offset:2048
	ds_read_b128 v[202:205], v201 offset:3072
	s_add_u32 s66, s66, 0x38000
	s_addc_u32 s67, s67, 0
	s_mov_b32 m0, s36
	v_lshl_add_u64 v[242:243], s[66:67], 0, v[136:137]
	ds_read_b128 v[206:209], v169 offset:32768
	ds_read_b128 v[210:213], v169 offset:33792
	ds_read_b128 v[214:217], v169 offset:34816
	ds_read_b128 v[218:221], v169 offset:35840
	ds_read_b128 v[222:225], v169 offset:36864
	ds_read_b128 v[226:229], v169 offset:37888
	ds_read_b128 v[230:233], v169 offset:38912
	ds_read_b128 v[234:237], v169 offset:39936
	global_load_lds_dwordx4 v[242:243], off
	v_lshl_add_u64 v[242:243], s[66:67], 0, v[132:133]
	s_mov_b32 m0, s37
	s_nop 0
	global_load_lds_dwordx4 v[242:243], off
	s_waitcnt vmcnt(8)
	s_waitcnt lgkmcnt(0)
	s_barrier
	s_setprio 1
	s_waitcnt lgkmcnt(0)
	v_mfma_f32_16x16x32_bf16 v[126:129], v[170:173], v[206:209], v[126:129]
	v_mfma_f32_16x16x32_bf16 v[122:125], v[178:181], v[206:209], v[122:125]
	v_mfma_f32_16x16x32_bf16 v[110:113], v[170:173], v[214:217], v[110:113]
	v_mfma_f32_16x16x32_bf16 v[106:109], v[178:181], v[214:217], v[106:109]
	v_mfma_f32_16x16x32_bf16 v[102:105], v[170:173], v[222:225], v[102:105]
	v_mfma_f32_16x16x32_bf16 v[98:101], v[178:181], v[222:225], v[98:101]
	v_mfma_f32_16x16x32_bf16 v[86:89], v[170:173], v[230:233], v[86:89]
	v_mfma_f32_16x16x32_bf16 v[82:85], v[178:181], v[230:233], v[82:85]
	v_mfma_f32_16x16x32_bf16 v[126:129], v[174:177], v[210:213], v[126:129]
	v_mfma_f32_16x16x32_bf16 v[122:125], v[182:185], v[210:213], v[122:125]
	v_mfma_f32_16x16x32_bf16 v[110:113], v[174:177], v[218:221], v[110:113]
	v_mfma_f32_16x16x32_bf16 v[106:109], v[182:185], v[218:221], v[106:109]
	v_mfma_f32_16x16x32_bf16 v[102:105], v[174:177], v[226:229], v[102:105]
	v_mfma_f32_16x16x32_bf16 v[98:101], v[182:185], v[226:229], v[98:101]
	v_mfma_f32_16x16x32_bf16 v[86:89], v[174:177], v[234:237], v[86:89]
	v_mfma_f32_16x16x32_bf16 v[82:85], v[182:185], v[234:237], v[82:85]
	s_setprio 0
	s_setprio 1
	v_mfma_f32_16x16x32_bf16 v[118:121], v[186:189], v[206:209], v[118:121]
	v_mfma_f32_16x16x32_bf16 v[114:117], v[194:197], v[206:209], v[114:117]
	v_mfma_f32_16x16x32_bf16 v[94:97], v[186:189], v[214:217], v[94:97]
	v_mfma_f32_16x16x32_bf16 v[90:93], v[194:197], v[214:217], v[90:93]
	v_mfma_f32_16x16x32_bf16 v[78:81], v[186:189], v[222:225], v[78:81]
	v_mfma_f32_16x16x32_bf16 v[74:77], v[194:197], v[222:225], v[74:77]
	v_mfma_f32_16x16x32_bf16 v[70:73], v[186:189], v[230:233], v[70:73]
	v_mfma_f32_16x16x32_bf16 v[66:69], v[194:197], v[230:233], v[66:69]
	v_mfma_f32_16x16x32_bf16 v[118:121], v[190:193], v[210:213], v[118:121]
	v_mfma_f32_16x16x32_bf16 v[114:117], v[202:205], v[210:213], v[114:117]
	v_mfma_f32_16x16x32_bf16 v[94:97], v[190:193], v[218:221], v[94:97]
	v_mfma_f32_16x16x32_bf16 v[90:93], v[202:205], v[218:221], v[90:93]
	v_mfma_f32_16x16x32_bf16 v[78:81], v[190:193], v[226:229], v[78:81]
	v_mfma_f32_16x16x32_bf16 v[74:77], v[202:205], v[226:229], v[74:77]
	v_mfma_f32_16x16x32_bf16 v[70:73], v[190:193], v[234:237], v[70:73]
	v_mfma_f32_16x16x32_bf16 v[66:69], v[202:205], v[234:237], v[66:69]
	s_setprio 0
	s_barrier
	s_add_i32 s66, s76, s21
	v_lshl_add_u64 v[146:147], v[146:147], 0, s[14:15]
	s_mov_b32 m0, s66
	ds_read_b128 v[206:209], v169 offset:49152
	ds_read_b128 v[210:213], v169 offset:50176
	ds_read_b128 v[214:217], v169 offset:51200
	ds_read_b128 v[218:221], v169 offset:52224
	ds_read_b128 v[222:225], v169 offset:53248
	ds_read_b128 v[226:229], v169 offset:54272
	ds_read_b128 v[230:233], v169 offset:55296
	ds_read_b128 v[234:237], v169 offset:56320
	global_load_lds_dwordx4 v[146:147], off
	s_add_i32 m0, s66, 0x2000
	s_add_u32 s54, s54, 0x38080
	v_lshl_add_u64 v[146:147], v[198:199], 0, s[14:15]
	s_addc_u32 s55, s55, 0
	s_add_i32 s66, s77, s21
	global_load_lds_dwordx4 v[146:147], off
	v_lshl_add_u64 v[146:147], s[54:55], 0, v[134:135]
	s_mov_b32 m0, s66
	s_nop 0
	global_load_lds_dwordx4 v[146:147], off
	v_lshl_add_u64 v[146:147], s[54:55], 0, v[130:131]
	s_add_i32 m0, s66, 0x2000
	s_nop 0
	global_load_lds_dwordx4 v[146:147], off
	v_lshl_add_u64 v[146:147], v[238:239], 0, s[14:15]
	s_mov_b32 m0, s39
	s_nop 0
	global_load_lds_dwordx4 v[146:147], off
	v_lshl_add_u64 v[146:147], v[240:241], 0, s[14:15]
	s_mov_b32 m0, s52
	s_nop 0
	global_load_lds_dwordx4 v[146:147], off
	s_waitcnt vmcnt(8)
	s_waitcnt lgkmcnt(0)
	s_barrier
	s_setprio 1
	s_waitcnt lgkmcnt(0)
	v_mfma_f32_16x16x32_bf16 v[62:65], v[170:173], v[206:209], v[62:65]
	v_mfma_f32_16x16x32_bf16 v[58:61], v[178:181], v[206:209], v[58:61]
	v_mfma_f32_16x16x32_bf16 v[54:57], v[170:173], v[214:217], v[54:57]
	v_mfma_f32_16x16x32_bf16 v[50:53], v[178:181], v[214:217], v[50:53]
	v_mfma_f32_16x16x32_bf16 v[38:41], v[170:173], v[222:225], v[38:41]
	v_mfma_f32_16x16x32_bf16 v[34:37], v[178:181], v[222:225], v[34:37]
	v_mfma_f32_16x16x32_bf16 v[22:25], v[170:173], v[230:233], v[22:25]
	v_mfma_f32_16x16x32_bf16 v[18:21], v[178:181], v[230:233], v[18:21]
	v_mfma_f32_16x16x32_bf16 v[62:65], v[174:177], v[210:213], v[62:65]
	v_mfma_f32_16x16x32_bf16 v[58:61], v[182:185], v[210:213], v[58:61]
	v_mfma_f32_16x16x32_bf16 v[54:57], v[174:177], v[218:221], v[54:57]
	v_mfma_f32_16x16x32_bf16 v[50:53], v[182:185], v[218:221], v[50:53]
	v_mfma_f32_16x16x32_bf16 v[38:41], v[174:177], v[226:229], v[38:41]
	v_mfma_f32_16x16x32_bf16 v[34:37], v[182:185], v[226:229], v[34:37]
	v_mfma_f32_16x16x32_bf16 v[22:25], v[174:177], v[234:237], v[22:25]
	v_mfma_f32_16x16x32_bf16 v[18:21], v[182:185], v[234:237], v[18:21]
	s_setprio 0
	s_setprio 1
	v_mfma_f32_16x16x32_bf16 v[46:49], v[186:189], v[206:209], v[46:49]
	v_mfma_f32_16x16x32_bf16 v[42:45], v[194:197], v[206:209], v[42:45]
	v_mfma_f32_16x16x32_bf16 v[30:33], v[186:189], v[214:217], v[30:33]
	v_mfma_f32_16x16x32_bf16 v[26:29], v[194:197], v[214:217], v[26:29]
	v_mfma_f32_16x16x32_bf16 v[14:17], v[186:189], v[222:225], v[14:17]
	v_mfma_f32_16x16x32_bf16 v[10:13], v[194:197], v[222:225], v[10:13]
	v_mfma_f32_16x16x32_bf16 v[6:9], v[186:189], v[230:233], v[6:9]
	v_mfma_f32_16x16x32_bf16 v[2:5], v[194:197], v[230:233], v[2:5]
	v_mfma_f32_16x16x32_bf16 v[46:49], v[190:193], v[210:213], v[46:49]
	v_mfma_f32_16x16x32_bf16 v[42:45], v[202:205], v[210:213], v[42:45]
	v_mfma_f32_16x16x32_bf16 v[30:33], v[190:193], v[218:221], v[30:33]
	v_mfma_f32_16x16x32_bf16 v[26:29], v[202:205], v[218:221], v[26:29]
	v_mfma_f32_16x16x32_bf16 v[14:17], v[190:193], v[226:229], v[14:17]
	v_mfma_f32_16x16x32_bf16 v[10:13], v[202:205], v[226:229], v[10:13]
	v_mfma_f32_16x16x32_bf16 v[6:9], v[190:193], v[234:237], v[6:9]
	v_mfma_f32_16x16x32_bf16 v[2:5], v[202:205], v[234:237], v[2:5]
	s_setprio 0
	s_barrier
	s_add_i32 s75, s75, 2
	s_add_u32 s30, s30, 0x100
	s_addc_u32 s31, s31, 0
	s_add_u32 s73, s73, 0x100
	s_addc_u32 s74, s74, 0

.LBB0_877:
	s_ashr_i32 s25, s24, 31
	s_lshl_b64 s[30:31], s[24:25], 18
	s_add_u32 s30, s50, s30
	s_addc_u32 s31, s51, s31
	s_and_b64 s[64:65], s[4:5], exec
	s_cselect_b32 s25, s31, s69
	s_cselect_b32 s77, s30, s68
	s_ashr_i32 s23, s22, 31
	s_lshl_b64 s[64:65], s[22:23], 18
	s_add_u32 s64, s26, s64
	s_addc_u32 s65, s27, s65
	s_and_b64 s[70:71], s[4:5], exec
	s_cselect_b32 s23, s65, s55
	s_cselect_b32 s78, s64, s54
	s_add_u32 s68, s68, 0x20080
	s_addc_u32 s69, s69, 0
	s_add_u32 s79, s54, 0x100
	s_addc_u32 s80, s55, 0
	s_mov_b32 s81, -2
	ds_read_b128 v[152:155], v148
	ds_read_b128 v[156:159], v148 offset:1024
	ds_read_b128 v[166:169], v148 offset:2048
	ds_read_b128 v[170:173], v148 offset:3072
	ds_read_b128 v[174:177], v149
	ds_read_b128 v[178:181], v149 offset:1024
	ds_read_b128 v[182:185], v149 offset:2048
	ds_read_b128 v[186:189], v149 offset:3072
	s_add_u32 s54, s68, 0xfffe0080
	s_addc_u32 s55, s69, -1
	s_cmp_eq_u32 s81, 4
	s_cselect_b32 s71, s25, s55
	s_cselect_b32 s70, s77, s54
	s_cselect_b32 s55, s23, s80
	s_cselect_b32 s54, s78, s79
	v_lshl_add_u64 v[160:161], s[68:69], 0, v[138:139]
	s_add_i32 m0, s36, 0xc000
	ds_read_b128 v[190:193], v150
	ds_read_b128 v[194:197], v150 offset:1024
	ds_read_b128 v[202:205], v150 offset:2048
	ds_read_b128 v[206:209], v150 offset:3072
	ds_read_b128 v[210:213], v150 offset:4096
	ds_read_b128 v[214:217], v150 offset:5120
	ds_read_b128 v[218:221], v150 offset:6144
	ds_read_b128 v[222:225], v150 offset:7168
	global_load_lds_dwordx4 v[160:161], off
	v_lshl_add_u64 v[160:161], s[68:69], 0, v[140:141]
	s_add_i32 m0, s36, 0xe000
	s_nop 0
	global_load_lds_dwordx4 v[160:161], off
	s_waitcnt vmcnt(8)
	s_waitcnt lgkmcnt(0)
	s_barrier
	s_setprio 1
	s_waitcnt lgkmcnt(0)
	v_mfma_f32_16x16x32_bf16 v[126:129], v[152:155], v[190:193], 0
	v_mfma_f32_16x16x32_bf16 v[122:125], v[166:169], v[190:193], 0
	v_mfma_f32_16x16x32_bf16 v[110:113], v[152:155], v[202:205], 0
	v_mfma_f32_16x16x32_bf16 v[106:109], v[166:169], v[202:205], 0
	v_mfma_f32_16x16x32_bf16 v[94:97], v[152:155], v[210:213], 0
	v_mfma_f32_16x16x32_bf16 v[90:93], v[166:169], v[210:213], 0
	v_mfma_f32_16x16x32_bf16 v[78:81], v[152:155], v[218:221], 0
	v_mfma_f32_16x16x32_bf16 v[74:77], v[166:169], v[218:221], 0
	v_mfma_f32_16x16x32_bf16 v[126:129], v[156:159], v[194:197], v[126:129]
	v_mfma_f32_16x16x32_bf16 v[122:125], v[170:173], v[194:197], v[122:125]
	v_mfma_f32_16x16x32_bf16 v[110:113], v[156:159], v[206:209], v[110:113]
	v_mfma_f32_16x16x32_bf16 v[106:109], v[170:173], v[206:209], v[106:109]
	v_mfma_f32_16x16x32_bf16 v[94:97], v[156:159], v[214:217], v[94:97]
	v_mfma_f32_16x16x32_bf16 v[90:93], v[170:173], v[214:217], v[90:93]
	v_mfma_f32_16x16x32_bf16 v[78:81], v[156:159], v[222:225], v[78:81]
	v_mfma_f32_16x16x32_bf16 v[74:77], v[170:173], v[222:225], v[74:77]
	s_setprio 0
	s_setprio 1
	v_mfma_f32_16x16x32_bf16 v[118:121], v[174:177], v[190:193], 0
	v_mfma_f32_16x16x32_bf16 v[114:117], v[182:185], v[190:193], 0
	v_mfma_f32_16x16x32_bf16 v[102:105], v[174:177], v[202:205], 0
	v_mfma_f32_16x16x32_bf16 v[98:101], v[182:185], v[202:205], 0
	v_mfma_f32_16x16x32_bf16 v[86:89], v[174:177], v[210:213], 0
	v_mfma_f32_16x16x32_bf16 v[82:85], v[182:185], v[210:213], 0
	v_mfma_f32_16x16x32_bf16 v[70:73], v[174:177], v[218:221], 0
	v_mfma_f32_16x16x32_bf16 v[66:69], v[182:185], v[218:221], 0
	v_mfma_f32_16x16x32_bf16 v[118:121], v[178:181], v[194:197], v[118:121]
	v_mfma_f32_16x16x32_bf16 v[114:117], v[186:189], v[194:197], v[114:117]
	v_mfma_f32_16x16x32_bf16 v[102:105], v[178:181], v[206:209], v[102:105]
	v_mfma_f32_16x16x32_bf16 v[98:101], v[186:189], v[206:209], v[98:101]
	v_mfma_f32_16x16x32_bf16 v[86:89], v[178:181], v[214:217], v[86:89]
	v_mfma_f32_16x16x32_bf16 v[82:85], v[186:189], v[214:217], v[82:85]
	v_mfma_f32_16x16x32_bf16 v[70:73], v[178:181], v[222:225], v[70:73]
	v_mfma_f32_16x16x32_bf16 v[66:69], v[186:189], v[222:225], v[66:69]
	s_setprio 0
	s_barrier
	s_add_i32 s82, s73, s2
	v_lshl_add_u64 v[160:161], s[54:55], 0, v[132:133]
	s_mov_b32 m0, s82
	ds_read_b128 v[190:193], v150 offset:16384
	ds_read_b128 v[194:197], v150 offset:17408
	ds_read_b128 v[202:205], v150 offset:18432
	ds_read_b128 v[206:209], v150 offset:19456
	ds_read_b128 v[210:213], v150 offset:20480
	ds_read_b128 v[214:217], v150 offset:21504
	ds_read_b128 v[218:221], v150 offset:22528
	ds_read_b128 v[222:225], v150 offset:23552
	global_load_lds_dwordx4 v[160:161], off
	s_add_i32 m0, s82, 0x2000
	s_add_u32 s82, s54, 0x20000
	v_lshl_add_u64 v[198:199], s[54:55], 0, v[136:137]
	s_addc_u32 s83, s55, 0
	s_add_i32 s84, s74, s2
	global_load_lds_dwordx4 v[198:199], off
	v_lshl_add_u64 v[226:227], s[82:83], 0, v[132:133]
	s_mov_b32 m0, s84
	v_lshl_add_u64 v[228:229], s[70:71], 0, v[134:135]
	global_load_lds_dwordx4 v[226:227], off
	v_lshl_add_u64 v[226:227], s[82:83], 0, v[136:137]
	s_add_i32 m0, s84, 0x2000
	s_nop 0
	global_load_lds_dwordx4 v[226:227], off
	v_lshl_add_u64 v[226:227], s[70:71], 0, v[130:131]
	s_mov_b32 m0, s36
	s_nop 0
	global_load_lds_dwordx4 v[226:227], off
	s_mov_b32 m0, s37
	s_nop 0
	global_load_lds_dwordx4 v[228:229], off
	s_waitcnt vmcnt(8)
	s_waitcnt lgkmcnt(0)
	s_barrier
	s_setprio 1
	s_waitcnt lgkmcnt(0)
	v_mfma_f32_16x16x32_bf16 v[62:65], v[152:155], v[190:193], 0
	v_mfma_f32_16x16x32_bf16 v[58:61], v[166:169], v[190:193], 0
	v_mfma_f32_16x16x32_bf16 v[46:49], v[152:155], v[202:205], 0
	v_mfma_f32_16x16x32_bf16 v[42:45], v[166:169], v[202:205], 0
	v_mfma_f32_16x16x32_bf16 v[30:33], v[152:155], v[210:213], 0
	v_mfma_f32_16x16x32_bf16 v[26:29], v[166:169], v[210:213], 0
	v_mfma_f32_16x16x32_bf16 v[14:17], v[152:155], v[218:221], 0
	v_mfma_f32_16x16x32_bf16 v[10:13], v[166:169], v[218:221], 0
	v_mfma_f32_16x16x32_bf16 v[62:65], v[156:159], v[194:197], v[62:65]
	v_mfma_f32_16x16x32_bf16 v[58:61], v[170:173], v[194:197], v[58:61]
	v_mfma_f32_16x16x32_bf16 v[46:49], v[156:159], v[206:209], v[46:49]
	v_mfma_f32_16x16x32_bf16 v[42:45], v[170:173], v[206:209], v[42:45]
	v_mfma_f32_16x16x32_bf16 v[30:33], v[156:159], v[214:217], v[30:33]
	v_mfma_f32_16x16x32_bf16 v[26:29], v[170:173], v[214:217], v[26:29]
	v_mfma_f32_16x16x32_bf16 v[14:17], v[156:159], v[222:225], v[14:17]
	v_mfma_f32_16x16x32_bf16 v[10:13], v[170:173], v[222:225], v[10:13]
	s_setprio 0
	s_setprio 1
	v_mfma_f32_16x16x32_bf16 v[54:57], v[174:177], v[190:193], 0
	v_mfma_f32_16x16x32_bf16 v[50:53], v[182:185], v[190:193], 0
	v_mfma_f32_16x16x32_bf16 v[38:41], v[174:177], v[202:205], 0
	v_mfma_f32_16x16x32_bf16 v[34:37], v[182:185], v[202:205], 0
	v_mfma_f32_16x16x32_bf16 v[22:25], v[174:177], v[210:213], 0
	v_mfma_f32_16x16x32_bf16 v[18:21], v[182:185], v[210:213], 0
	v_mfma_f32_16x16x32_bf16 v[6:9], v[174:177], v[218:221], 0
	v_mfma_f32_16x16x32_bf16 v[2:5], v[182:185], v[218:221], 0
	v_mfma_f32_16x16x32_bf16 v[54:57], v[178:181], v[194:197], v[54:57]
	v_mfma_f32_16x16x32_bf16 v[50:53], v[186:189], v[194:197], v[50:53]
	v_mfma_f32_16x16x32_bf16 v[38:41], v[178:181], v[206:209], v[38:41]
	v_mfma_f32_16x16x32_bf16 v[34:37], v[186:189], v[206:209], v[34:37]
	v_mfma_f32_16x16x32_bf16 v[22:25], v[178:181], v[214:217], v[22:25]
	v_mfma_f32_16x16x32_bf16 v[18:21], v[186:189], v[214:217], v[18:21]
	v_mfma_f32_16x16x32_bf16 v[6:9], v[178:181], v[222:225], v[6:9]
	v_mfma_f32_16x16x32_bf16 v[2:5], v[186:189], v[222:225], v[2:5]
	s_setprio 0
	s_barrier
	s_add_i32 s82, 0, 0x18000
	v_add_u32_e32 v163, s82, v147
	s_add_i32 s83, 0, 0x1c000
	ds_read_b128 v[152:155], v163
	ds_read_b128 v[156:159], v163 offset:1024
	ds_read_b128 v[166:169], v163 offset:2048
	ds_read_b128 v[170:173], v163 offset:3072
	v_add_u32_e32 v163, s83, v147
	ds_read_b128 v[174:177], v163
	ds_read_b128 v[178:181], v163 offset:1024
	ds_read_b128 v[182:185], v163 offset:2048
	ds_read_b128 v[186:189], v163 offset:3072
	s_add_u32 s70, s70, 0x20000
	s_addc_u32 s71, s71, 0
	s_mov_b32 m0, s38
	v_lshl_add_u64 v[230:231], s[70:71], 0, v[130:131]
	ds_read_b128 v[190:193], v150 offset:32768
	ds_read_b128 v[194:197], v150 offset:33792
	ds_read_b128 v[202:205], v150 offset:34816
	ds_read_b128 v[206:209], v150 offset:35840
	ds_read_b128 v[210:213], v150 offset:36864
	ds_read_b128 v[214:217], v150 offset:37888
	ds_read_b128 v[218:221], v150 offset:38912
	ds_read_b128 v[222:225], v150 offset:39936
	global_load_lds_dwordx4 v[230:231], off
	v_lshl_add_u64 v[230:231], s[70:71], 0, v[134:135]
	s_mov_b32 m0, s39
	s_nop 0
	global_load_lds_dwordx4 v[230:231], off
	s_waitcnt vmcnt(8)
	s_waitcnt lgkmcnt(0)
	s_barrier
	s_setprio 1
	s_waitcnt lgkmcnt(0)
	v_mfma_f32_16x16x32_bf16 v[126:129], v[152:155], v[190:193], v[126:129]
	v_mfma_f32_16x16x32_bf16 v[122:125], v[166:169], v[190:193], v[122:125]
	v_mfma_f32_16x16x32_bf16 v[110:113], v[152:155], v[202:205], v[110:113]
	v_mfma_f32_16x16x32_bf16 v[106:109], v[166:169], v[202:205], v[106:109]
	v_mfma_f32_16x16x32_bf16 v[94:97], v[152:155], v[210:213], v[94:97]
	v_mfma_f32_16x16x32_bf16 v[90:93], v[166:169], v[210:213], v[90:93]
	v_mfma_f32_16x16x32_bf16 v[78:81], v[152:155], v[218:221], v[78:81]
	v_mfma_f32_16x16x32_bf16 v[74:77], v[166:169], v[218:221], v[74:77]
	v_mfma_f32_16x16x32_bf16 v[126:129], v[156:159], v[194:197], v[126:129]
	v_mfma_f32_16x16x32_bf16 v[122:125], v[170:173], v[194:197], v[122:125]
	v_mfma_f32_16x16x32_bf16 v[110:113], v[156:159], v[206:209], v[110:113]
	v_mfma_f32_16x16x32_bf16 v[106:109], v[170:173], v[206:209], v[106:109]
	v_mfma_f32_16x16x32_bf16 v[94:97], v[156:159], v[214:217], v[94:97]
	v_mfma_f32_16x16x32_bf16 v[90:93], v[170:173], v[214:217], v[90:93]
	v_mfma_f32_16x16x32_bf16 v[78:81], v[156:159], v[222:225], v[78:81]
	v_mfma_f32_16x16x32_bf16 v[74:77], v[170:173], v[222:225], v[74:77]
	s_setprio 0
	s_setprio 1
	v_mfma_f32_16x16x32_bf16 v[118:121], v[174:177], v[190:193], v[118:121]
	v_mfma_f32_16x16x32_bf16 v[114:117], v[182:185], v[190:193], v[114:117]
	v_mfma_f32_16x16x32_bf16 v[102:105], v[174:177], v[202:205], v[102:105]
	v_mfma_f32_16x16x32_bf16 v[98:101], v[182:185], v[202:205], v[98:101]
	v_mfma_f32_16x16x32_bf16 v[86:89], v[174:177], v[210:213], v[86:89]
	v_mfma_f32_16x16x32_bf16 v[82:85], v[182:185], v[210:213], v[82:85]
	v_mfma_f32_16x16x32_bf16 v[70:73], v[174:177], v[218:221], v[70:73]
	v_mfma_f32_16x16x32_bf16 v[66:69], v[182:185], v[218:221], v[66:69]
	v_mfma_f32_16x16x32_bf16 v[118:121], v[178:181], v[194:197], v[118:121]
	v_mfma_f32_16x16x32_bf16 v[114:117], v[186:189], v[194:197], v[114:117]
	v_mfma_f32_16x16x32_bf16 v[102:105], v[178:181], v[206:209], v[102:105]
	v_mfma_f32_16x16x32_bf16 v[98:101], v[186:189], v[206:209], v[98:101]
	v_mfma_f32_16x16x32_bf16 v[86:89], v[178:181], v[214:217], v[86:89]
	v_mfma_f32_16x16x32_bf16 v[82:85], v[186:189], v[214:217], v[82:85]
	v_mfma_f32_16x16x32_bf16 v[70:73], v[178:181], v[222:225], v[70:73]
	v_mfma_f32_16x16x32_bf16 v[66:69], v[186:189], v[222:225], v[66:69]
	s_setprio 0
	s_barrier
	s_add_i32 s70, s82, s2
	v_lshl_add_u64 v[160:161], v[160:161], 0, s[10:11]
	s_mov_b32 m0, s70
	ds_read_b128 v[190:193], v150 offset:49152
	ds_read_b128 v[194:197], v150 offset:50176
	ds_read_b128 v[202:205], v150 offset:51200
	ds_read_b128 v[206:209], v150 offset:52224
	ds_read_b128 v[210:213], v150 offset:53248
	ds_read_b128 v[214:217], v150 offset:54272
	ds_read_b128 v[218:221], v150 offset:55296
	ds_read_b128 v[222:225], v150 offset:56320
	global_load_lds_dwordx4 v[160:161], off
	s_add_i32 m0, s70, 0x2000
	s_add_u32 s54, s54, 0x20080
	v_lshl_add_u64 v[160:161], v[198:199], 0, s[10:11]
	s_addc_u32 s55, s55, 0
	s_add_i32 s70, s83, s2
	global_load_lds_dwordx4 v[160:161], off
	v_lshl_add_u64 v[160:161], s[54:55], 0, v[132:133]
	s_mov_b32 m0, s70
	s_nop 0
	global_load_lds_dwordx4 v[160:161], off
	v_lshl_add_u64 v[160:161], s[54:55], 0, v[136:137]
	s_add_i32 m0, s70, 0x2000
	s_nop 0
	global_load_lds_dwordx4 v[160:161], off
	v_lshl_add_u64 v[160:161], v[226:227], 0, s[10:11]
	s_mov_b32 m0, s57
	s_nop 0
	global_load_lds_dwordx4 v[160:161], off
	v_lshl_add_u64 v[160:161], v[228:229], 0, s[10:11]
	s_mov_b32 m0, s67
	s_nop 0
	global_load_lds_dwordx4 v[160:161], off
	s_waitcnt vmcnt(8)
	s_waitcnt lgkmcnt(0)
	s_barrier
	s_setprio 1
	s_waitcnt lgkmcnt(0)
	v_mfma_f32_16x16x32_bf16 v[62:65], v[152:155], v[190:193], v[62:65]
	v_mfma_f32_16x16x32_bf16 v[58:61], v[166:169], v[190:193], v[58:61]
	v_mfma_f32_16x16x32_bf16 v[46:49], v[152:155], v[202:205], v[46:49]
	v_mfma_f32_16x16x32_bf16 v[42:45], v[166:169], v[202:205], v[42:45]
	v_mfma_f32_16x16x32_bf16 v[30:33], v[152:155], v[210:213], v[30:33]
	v_mfma_f32_16x16x32_bf16 v[26:29], v[166:169], v[210:213], v[26:29]
	v_mfma_f32_16x16x32_bf16 v[14:17], v[152:155], v[218:221], v[14:17]
	v_mfma_f32_16x16x32_bf16 v[10:13], v[166:169], v[218:221], v[10:13]
	v_mfma_f32_16x16x32_bf16 v[62:65], v[156:159], v[194:197], v[62:65]
	v_mfma_f32_16x16x32_bf16 v[58:61], v[170:173], v[194:197], v[58:61]
	v_mfma_f32_16x16x32_bf16 v[46:49], v[156:159], v[206:209], v[46:49]
	v_mfma_f32_16x16x32_bf16 v[42:45], v[170:173], v[206:209], v[42:45]
	v_mfma_f32_16x16x32_bf16 v[30:33], v[156:159], v[214:217], v[30:33]
	v_mfma_f32_16x16x32_bf16 v[26:29], v[170:173], v[214:217], v[26:29]
	v_mfma_f32_16x16x32_bf16 v[14:17], v[156:159], v[222:225], v[14:17]
	v_mfma_f32_16x16x32_bf16 v[10:13], v[170:173], v[222:225], v[10:13]
	s_setprio 0
	s_setprio 1
	v_mfma_f32_16x16x32_bf16 v[54:57], v[174:177], v[190:193], v[54:57]
	v_mfma_f32_16x16x32_bf16 v[50:53], v[182:185], v[190:193], v[50:53]
	v_mfma_f32_16x16x32_bf16 v[38:41], v[174:177], v[202:205], v[38:41]
	v_mfma_f32_16x16x32_bf16 v[34:37], v[182:185], v[202:205], v[34:37]
	v_mfma_f32_16x16x32_bf16 v[22:25], v[174:177], v[210:213], v[22:25]
	v_mfma_f32_16x16x32_bf16 v[18:21], v[182:185], v[210:213], v[18:21]
	v_mfma_f32_16x16x32_bf16 v[6:9], v[174:177], v[218:221], v[6:9]
	v_mfma_f32_16x16x32_bf16 v[2:5], v[182:185], v[218:221], v[2:5]
	v_mfma_f32_16x16x32_bf16 v[54:57], v[178:181], v[194:197], v[54:57]
	v_mfma_f32_16x16x32_bf16 v[50:53], v[186:189], v[194:197], v[50:53]
	v_mfma_f32_16x16x32_bf16 v[38:41], v[178:181], v[206:209], v[38:41]
	v_mfma_f32_16x16x32_bf16 v[34:37], v[186:189], v[206:209], v[34:37]
	v_mfma_f32_16x16x32_bf16 v[22:25], v[178:181], v[214:217], v[22:25]
	v_mfma_f32_16x16x32_bf16 v[18:21], v[186:189], v[214:217], v[18:21]
	v_mfma_f32_16x16x32_bf16 v[6:9], v[178:181], v[222:225], v[6:9]
	v_mfma_f32_16x16x32_bf16 v[2:5], v[186:189], v[222:225], v[2:5]
	s_setprio 0
	s_barrier
	s_add_i32 s81, s81, 2
	s_add_u32 s68, s68, 0x100
	s_addc_u32 s69, s69, 0
	s_add_u32 s79, s79, 0x100
	s_addc_u32 s80, s80, 0

.LBB0_1630:
	s_ashr_i32 s63, s62, 31
	s_lshl_b64 s[50:51], s[62:63], 21
	s_add_u32 s54, s46, s50
	s_addc_u32 s55, s47, s51
	s_ashr_i32 s59, s58, 31
	s_lshl_b64 s[50:51], s[58:59], 11
	s_add_u32 s70, s54, s50
	s_addc_u32 s71, s55, s51
	s_and_b64 s[54:55], s[68:69], exec
	s_cselect_b32 s54, s71, s81
	s_cselect_b32 s55, s70, s80
	s_ashr_i32 s61, s60, 31
	s_lshl_b64 s[56:57], s[60:61], 21
	v_readlane_b32 s64, v250, 13
	v_readlane_b32 s65, v250, 14
	s_add_u32 s56, s64, s56
	s_addc_u32 s57, s65, s57
	s_add_u32 s72, s56, s50
	s_addc_u32 s73, s57, s51
	s_and_b64 s[50:51], s[68:69], exec
	s_cselect_b32 s59, s73, s83
	s_cselect_b32 s61, s72, s82
	s_add_u32 s80, s80, 0x100080
	s_addc_u32 s81, s81, 0
	s_add_u32 s63, s82, 0x100
	s_addc_u32 s64, s83, 0
	s_mov_b32 s65, -2
	ds_read_b128 v[150:153], v146
	ds_read_b128 v[154:157], v146 offset:1024
	ds_read_b128 v[158:161], v146 offset:2048
	ds_read_b128 v[166:169], v146 offset:3072
	ds_read_b128 v[170:173], v147
	ds_read_b128 v[174:177], v147 offset:1024
	ds_read_b128 v[178:181], v147 offset:2048
	ds_read_b128 v[182:185], v147 offset:3072
	s_add_u32 s50, s80, 0xfff00080
	s_addc_u32 s51, s81, -1
	s_cmp_eq_u32 s65, 12
	s_cselect_b32 s85, s54, s51
	s_cselect_b32 s84, s55, s50
	s_cselect_b32 s83, s59, s64
	s_cselect_b32 s82, s61, s63
	v_lshl_add_u64 v[198:199], s[80:81], 0, v[138:139]
	s_add_i32 m0, s15, 0xc000
	ds_read_b128 v[186:189], v148
	ds_read_b128 v[190:193], v148 offset:1024
	ds_read_b128 v[194:197], v148 offset:2048
	ds_read_b128 v[210:213], v148 offset:3072
	ds_read_b128 v[214:217], v148 offset:4096
	ds_read_b128 v[218:221], v148 offset:5120
	ds_read_b128 v[222:225], v148 offset:6144
	ds_read_b128 v[226:229], v148 offset:7168
	global_load_lds_dwordx4 v[198:199], off
	v_lshl_add_u64 v[198:199], s[80:81], 0, v[140:141]
	s_add_i32 m0, s15, 0xe000
	s_nop 0
	global_load_lds_dwordx4 v[198:199], off
	s_waitcnt vmcnt(8)
	s_waitcnt lgkmcnt(0)
	s_barrier
	s_setprio 1
	s_waitcnt lgkmcnt(0)
	v_mfma_f32_16x16x32_bf16 v[126:129], v[150:153], v[186:189], 0
	v_mfma_f32_16x16x32_bf16 v[122:125], v[158:161], v[186:189], 0
	v_mfma_f32_16x16x32_bf16 v[110:113], v[150:153], v[194:197], 0
	v_mfma_f32_16x16x32_bf16 v[106:109], v[158:161], v[194:197], 0
	v_mfma_f32_16x16x32_bf16 v[94:97], v[150:153], v[214:217], 0
	v_mfma_f32_16x16x32_bf16 v[90:93], v[158:161], v[214:217], 0
	v_mfma_f32_16x16x32_bf16 v[78:81], v[150:153], v[222:225], 0
	v_mfma_f32_16x16x32_bf16 v[74:77], v[158:161], v[222:225], 0
	v_mfma_f32_16x16x32_bf16 v[126:129], v[154:157], v[190:193], v[126:129]
	v_mfma_f32_16x16x32_bf16 v[122:125], v[166:169], v[190:193], v[122:125]
	v_mfma_f32_16x16x32_bf16 v[110:113], v[154:157], v[210:213], v[110:113]
	v_mfma_f32_16x16x32_bf16 v[106:109], v[166:169], v[210:213], v[106:109]
	v_mfma_f32_16x16x32_bf16 v[94:97], v[154:157], v[218:221], v[94:97]
	v_mfma_f32_16x16x32_bf16 v[90:93], v[166:169], v[218:221], v[90:93]
	v_mfma_f32_16x16x32_bf16 v[78:81], v[154:157], v[226:229], v[78:81]
	v_mfma_f32_16x16x32_bf16 v[74:77], v[166:169], v[226:229], v[74:77]
	s_setprio 0
	s_setprio 1
	v_mfma_f32_16x16x32_bf16 v[118:121], v[170:173], v[186:189], 0
	v_mfma_f32_16x16x32_bf16 v[114:117], v[178:181], v[186:189], 0
	v_mfma_f32_16x16x32_bf16 v[102:105], v[170:173], v[194:197], 0
	v_mfma_f32_16x16x32_bf16 v[98:101], v[178:181], v[194:197], 0
	v_mfma_f32_16x16x32_bf16 v[86:89], v[170:173], v[214:217], 0
	v_mfma_f32_16x16x32_bf16 v[82:85], v[178:181], v[214:217], 0
	v_mfma_f32_16x16x32_bf16 v[70:73], v[170:173], v[222:225], 0
	v_mfma_f32_16x16x32_bf16 v[66:69], v[178:181], v[222:225], 0
	v_mfma_f32_16x16x32_bf16 v[118:121], v[174:177], v[190:193], v[118:121]
	v_mfma_f32_16x16x32_bf16 v[114:117], v[182:185], v[190:193], v[114:117]
	v_mfma_f32_16x16x32_bf16 v[102:105], v[174:177], v[210:213], v[102:105]
	v_mfma_f32_16x16x32_bf16 v[98:101], v[182:185], v[210:213], v[98:101]
	v_mfma_f32_16x16x32_bf16 v[86:89], v[174:177], v[218:221], v[86:89]
	v_mfma_f32_16x16x32_bf16 v[82:85], v[182:185], v[218:221], v[82:85]
	v_mfma_f32_16x16x32_bf16 v[70:73], v[174:177], v[226:229], v[70:73]
	v_mfma_f32_16x16x32_bf16 v[66:69], v[182:185], v[226:229], v[66:69]
	s_setprio 0
	s_barrier
	s_add_i32 s50, s9, s14
	v_lshl_add_u64 v[198:199], s[82:83], 0, v[134:135]
	s_mov_b32 m0, s50
	ds_read_b128 v[186:189], v148 offset:16384
	ds_read_b128 v[190:193], v148 offset:17408
	ds_read_b128 v[194:197], v148 offset:18432
	ds_read_b128 v[210:213], v148 offset:19456
	ds_read_b128 v[214:217], v148 offset:20480
	ds_read_b128 v[218:221], v148 offset:21504
	ds_read_b128 v[222:225], v148 offset:22528
	ds_read_b128 v[226:229], v148 offset:23552
	global_load_lds_dwordx4 v[198:199], off
	s_add_i32 m0, s50, 0x2000
	s_add_u32 s50, s82, 0x100000
	v_lshl_add_u64 v[230:231], s[82:83], 0, v[130:131]
	s_addc_u32 s51, s83, 0
	s_add_i32 s56, s33, s14
	global_load_lds_dwordx4 v[230:231], off
	v_lshl_add_u64 v[232:233], s[50:51], 0, v[134:135]
	s_mov_b32 m0, s56
	v_lshl_add_u64 v[234:235], s[84:85], 0, v[132:133]
	global_load_lds_dwordx4 v[232:233], off
	v_lshl_add_u64 v[232:233], s[50:51], 0, v[130:131]
	s_add_i32 m0, s56, 0x2000
	s_nop 0
	global_load_lds_dwordx4 v[232:233], off
	v_lshl_add_u64 v[232:233], s[84:85], 0, v[136:137]
	s_mov_b32 m0, s15
	s_nop 0
	global_load_lds_dwordx4 v[232:233], off
	s_mov_b32 m0, s20
	s_nop 0
	global_load_lds_dwordx4 v[234:235], off
	s_waitcnt vmcnt(8)
	s_waitcnt lgkmcnt(0)
	s_barrier
	s_setprio 1
	s_waitcnt lgkmcnt(0)
	v_mfma_f32_16x16x32_bf16 v[62:65], v[150:153], v[186:189], 0
	v_mfma_f32_16x16x32_bf16 v[58:61], v[158:161], v[186:189], 0
	v_mfma_f32_16x16x32_bf16 v[46:49], v[150:153], v[194:197], 0
	v_mfma_f32_16x16x32_bf16 v[42:45], v[158:161], v[194:197], 0
	v_mfma_f32_16x16x32_bf16 v[30:33], v[150:153], v[214:217], 0
	v_mfma_f32_16x16x32_bf16 v[26:29], v[158:161], v[214:217], 0
	v_mfma_f32_16x16x32_bf16 v[14:17], v[150:153], v[222:225], 0
	v_mfma_f32_16x16x32_bf16 v[10:13], v[158:161], v[222:225], 0
	v_mfma_f32_16x16x32_bf16 v[62:65], v[154:157], v[190:193], v[62:65]
	v_mfma_f32_16x16x32_bf16 v[58:61], v[166:169], v[190:193], v[58:61]
	v_mfma_f32_16x16x32_bf16 v[46:49], v[154:157], v[210:213], v[46:49]
	v_mfma_f32_16x16x32_bf16 v[42:45], v[166:169], v[210:213], v[42:45]
	v_mfma_f32_16x16x32_bf16 v[30:33], v[154:157], v[218:221], v[30:33]
	v_mfma_f32_16x16x32_bf16 v[26:29], v[166:169], v[218:221], v[26:29]
	v_mfma_f32_16x16x32_bf16 v[14:17], v[154:157], v[226:229], v[14:17]
	v_mfma_f32_16x16x32_bf16 v[10:13], v[166:169], v[226:229], v[10:13]
	s_setprio 0
	s_setprio 1
	v_mfma_f32_16x16x32_bf16 v[54:57], v[170:173], v[186:189], 0
	v_mfma_f32_16x16x32_bf16 v[50:53], v[178:181], v[186:189], 0
	v_mfma_f32_16x16x32_bf16 v[38:41], v[170:173], v[194:197], 0
	v_mfma_f32_16x16x32_bf16 v[34:37], v[178:181], v[194:197], 0
	v_mfma_f32_16x16x32_bf16 v[22:25], v[170:173], v[214:217], 0
	v_mfma_f32_16x16x32_bf16 v[18:21], v[178:181], v[214:217], 0
	v_mfma_f32_16x16x32_bf16 v[6:9], v[170:173], v[222:225], 0
	v_mfma_f32_16x16x32_bf16 v[2:5], v[178:181], v[222:225], 0
	v_mfma_f32_16x16x32_bf16 v[54:57], v[174:177], v[190:193], v[54:57]
	v_mfma_f32_16x16x32_bf16 v[50:53], v[182:185], v[190:193], v[50:53]
	v_mfma_f32_16x16x32_bf16 v[38:41], v[174:177], v[210:213], v[38:41]
	v_mfma_f32_16x16x32_bf16 v[34:37], v[182:185], v[210:213], v[34:37]
	v_mfma_f32_16x16x32_bf16 v[22:25], v[174:177], v[218:221], v[22:25]
	v_mfma_f32_16x16x32_bf16 v[18:21], v[182:185], v[218:221], v[18:21]
	v_mfma_f32_16x16x32_bf16 v[6:9], v[174:177], v[226:229], v[6:9]
	v_mfma_f32_16x16x32_bf16 v[2:5], v[182:185], v[226:229], v[2:5]
	s_setprio 0
	s_barrier
	s_add_i32 s56, 0, 0x18000
	s_add_i32 s57, 0, 0x1c000
	v_add_u32_e32 v166, s56, v145
	v_add_u32_e32 v182, s57, v145
	ds_read_b128 v[150:153], v166
	ds_read_b128 v[154:157], v166 offset:1024
	ds_read_b128 v[158:161], v166 offset:2048
	ds_read_b128 v[166:169], v166 offset:3072
	ds_read_b128 v[170:173], v182
	ds_read_b128 v[174:177], v182 offset:1024
	ds_read_b128 v[178:181], v182 offset:2048
	ds_read_b128 v[182:185], v182 offset:3072
	s_add_u32 s50, s84, 0x100000
	s_addc_u32 s51, s85, 0
	s_mov_b32 m0, s21
	v_lshl_add_u64 v[236:237], s[50:51], 0, v[136:137]
	ds_read_b128 v[186:189], v148 offset:32768
	ds_read_b128 v[190:193], v148 offset:33792
	ds_read_b128 v[194:197], v148 offset:34816
	ds_read_b128 v[210:213], v148 offset:35840
	ds_read_b128 v[214:217], v148 offset:36864
	ds_read_b128 v[218:221], v148 offset:37888
	ds_read_b128 v[222:225], v148 offset:38912
	ds_read_b128 v[226:229], v148 offset:39936
	global_load_lds_dwordx4 v[236:237], off
	v_lshl_add_u64 v[236:237], s[50:51], 0, v[132:133]
	s_mov_b32 m0, s26
	s_nop 0
	global_load_lds_dwordx4 v[236:237], off
	s_waitcnt vmcnt(8)
	s_waitcnt lgkmcnt(0)
	s_barrier
	s_setprio 1
	s_waitcnt lgkmcnt(0)
	v_mfma_f32_16x16x32_bf16 v[126:129], v[150:153], v[186:189], v[126:129]
	v_mfma_f32_16x16x32_bf16 v[122:125], v[158:161], v[186:189], v[122:125]
	v_mfma_f32_16x16x32_bf16 v[110:113], v[150:153], v[194:197], v[110:113]
	v_mfma_f32_16x16x32_bf16 v[106:109], v[158:161], v[194:197], v[106:109]
	v_mfma_f32_16x16x32_bf16 v[94:97], v[150:153], v[214:217], v[94:97]
	v_mfma_f32_16x16x32_bf16 v[90:93], v[158:161], v[214:217], v[90:93]
	v_mfma_f32_16x16x32_bf16 v[78:81], v[150:153], v[222:225], v[78:81]
	v_mfma_f32_16x16x32_bf16 v[74:77], v[158:161], v[222:225], v[74:77]
	v_mfma_f32_16x16x32_bf16 v[126:129], v[154:157], v[190:193], v[126:129]
	v_mfma_f32_16x16x32_bf16 v[122:125], v[166:169], v[190:193], v[122:125]
	v_mfma_f32_16x16x32_bf16 v[110:113], v[154:157], v[210:213], v[110:113]
	v_mfma_f32_16x16x32_bf16 v[106:109], v[166:169], v[210:213], v[106:109]
	v_mfma_f32_16x16x32_bf16 v[94:97], v[154:157], v[218:221], v[94:97]
	v_mfma_f32_16x16x32_bf16 v[90:93], v[166:169], v[218:221], v[90:93]
	v_mfma_f32_16x16x32_bf16 v[78:81], v[154:157], v[226:229], v[78:81]
	v_mfma_f32_16x16x32_bf16 v[74:77], v[166:169], v[226:229], v[74:77]
	s_setprio 0
	s_setprio 1
	v_mfma_f32_16x16x32_bf16 v[118:121], v[170:173], v[186:189], v[118:121]
	v_mfma_f32_16x16x32_bf16 v[114:117], v[178:181], v[186:189], v[114:117]
	v_mfma_f32_16x16x32_bf16 v[102:105], v[170:173], v[194:197], v[102:105]
	v_mfma_f32_16x16x32_bf16 v[98:101], v[178:181], v[194:197], v[98:101]
	v_mfma_f32_16x16x32_bf16 v[86:89], v[170:173], v[214:217], v[86:89]
	v_mfma_f32_16x16x32_bf16 v[82:85], v[178:181], v[214:217], v[82:85]
	v_mfma_f32_16x16x32_bf16 v[70:73], v[170:173], v[222:225], v[70:73]
	v_mfma_f32_16x16x32_bf16 v[66:69], v[178:181], v[222:225], v[66:69]
	v_mfma_f32_16x16x32_bf16 v[118:121], v[174:177], v[190:193], v[118:121]
	v_mfma_f32_16x16x32_bf16 v[114:117], v[182:185], v[190:193], v[114:117]
	v_mfma_f32_16x16x32_bf16 v[102:105], v[174:177], v[210:213], v[102:105]
	v_mfma_f32_16x16x32_bf16 v[98:101], v[182:185], v[210:213], v[98:101]
	v_mfma_f32_16x16x32_bf16 v[86:89], v[174:177], v[218:221], v[86:89]
	v_mfma_f32_16x16x32_bf16 v[82:85], v[182:185], v[218:221], v[82:85]
	v_mfma_f32_16x16x32_bf16 v[70:73], v[174:177], v[226:229], v[70:73]
	v_mfma_f32_16x16x32_bf16 v[66:69], v[182:185], v[226:229], v[66:69]
	s_setprio 0
	s_barrier
	s_add_i32 s50, s56, s14
	v_lshl_add_u64 v[198:199], v[198:199], 0, s[6:7]
	s_mov_b32 m0, s50
	ds_read_b128 v[186:189], v148 offset:49152
	ds_read_b128 v[190:193], v148 offset:50176
	ds_read_b128 v[194:197], v148 offset:51200
	ds_read_b128 v[210:213], v148 offset:52224
	ds_read_b128 v[214:217], v148 offset:53248
	ds_read_b128 v[218:221], v148 offset:54272
	ds_read_b128 v[222:225], v148 offset:55296
	ds_read_b128 v[226:229], v148 offset:56320
	global_load_lds_dwordx4 v[198:199], off
	s_add_i32 m0, s50, 0x2000
	s_add_u32 s50, s82, 0x100080
	v_lshl_add_u64 v[198:199], v[230:231], 0, s[6:7]
	s_addc_u32 s51, s83, 0
	s_add_i32 s56, s57, s14
	global_load_lds_dwordx4 v[198:199], off
	v_lshl_add_u64 v[198:199], s[50:51], 0, v[134:135]
	s_mov_b32 m0, s56
	s_nop 0
	global_load_lds_dwordx4 v[198:199], off
	v_lshl_add_u64 v[198:199], s[50:51], 0, v[130:131]
	s_add_i32 m0, s56, 0x2000
	s_nop 0
	global_load_lds_dwordx4 v[198:199], off
	v_lshl_add_u64 v[198:199], v[232:233], 0, s[6:7]
	s_mov_b32 m0, s37
	s_nop 0
	global_load_lds_dwordx4 v[198:199], off
	v_lshl_add_u64 v[198:199], v[234:235], 0, s[6:7]
	s_mov_b32 m0, s38
	s_nop 0
	global_load_lds_dwordx4 v[198:199], off
	s_waitcnt vmcnt(8)
	s_waitcnt lgkmcnt(0)
	s_barrier
	s_setprio 1
	s_waitcnt lgkmcnt(0)
	v_mfma_f32_16x16x32_bf16 v[62:65], v[150:153], v[186:189], v[62:65]
	v_mfma_f32_16x16x32_bf16 v[58:61], v[158:161], v[186:189], v[58:61]
	v_mfma_f32_16x16x32_bf16 v[46:49], v[150:153], v[194:197], v[46:49]
	v_mfma_f32_16x16x32_bf16 v[42:45], v[158:161], v[194:197], v[42:45]
	v_mfma_f32_16x16x32_bf16 v[30:33], v[150:153], v[214:217], v[30:33]
	v_mfma_f32_16x16x32_bf16 v[26:29], v[158:161], v[214:217], v[26:29]
	v_mfma_f32_16x16x32_bf16 v[14:17], v[150:153], v[222:225], v[14:17]
	v_mfma_f32_16x16x32_bf16 v[10:13], v[158:161], v[222:225], v[10:13]
	v_mfma_f32_16x16x32_bf16 v[62:65], v[154:157], v[190:193], v[62:65]
	v_mfma_f32_16x16x32_bf16 v[58:61], v[166:169], v[190:193], v[58:61]
	v_mfma_f32_16x16x32_bf16 v[46:49], v[154:157], v[210:213], v[46:49]
	v_mfma_f32_16x16x32_bf16 v[42:45], v[166:169], v[210:213], v[42:45]
	v_mfma_f32_16x16x32_bf16 v[30:33], v[154:157], v[218:221], v[30:33]
	v_mfma_f32_16x16x32_bf16 v[26:29], v[166:169], v[218:221], v[26:29]
	v_mfma_f32_16x16x32_bf16 v[14:17], v[154:157], v[226:229], v[14:17]
	v_mfma_f32_16x16x32_bf16 v[10:13], v[166:169], v[226:229], v[10:13]
	s_setprio 0
	s_setprio 1
	v_mfma_f32_16x16x32_bf16 v[54:57], v[170:173], v[186:189], v[54:57]
	v_mfma_f32_16x16x32_bf16 v[50:53], v[178:181], v[186:189], v[50:53]
	v_mfma_f32_16x16x32_bf16 v[38:41], v[170:173], v[194:197], v[38:41]
	v_mfma_f32_16x16x32_bf16 v[34:37], v[178:181], v[194:197], v[34:37]
	v_mfma_f32_16x16x32_bf16 v[22:25], v[170:173], v[214:217], v[22:25]
	v_mfma_f32_16x16x32_bf16 v[18:21], v[178:181], v[214:217], v[18:21]
	v_mfma_f32_16x16x32_bf16 v[6:9], v[170:173], v[222:225], v[6:9]
	v_mfma_f32_16x16x32_bf16 v[2:5], v[178:181], v[222:225], v[2:5]
	v_mfma_f32_16x16x32_bf16 v[54:57], v[174:177], v[190:193], v[54:57]
	v_mfma_f32_16x16x32_bf16 v[50:53], v[182:185], v[190:193], v[50:53]
	v_mfma_f32_16x16x32_bf16 v[38:41], v[174:177], v[210:213], v[38:41]
	v_mfma_f32_16x16x32_bf16 v[34:37], v[182:185], v[210:213], v[34:37]
	v_mfma_f32_16x16x32_bf16 v[22:25], v[174:177], v[218:221], v[22:25]
	v_mfma_f32_16x16x32_bf16 v[18:21], v[182:185], v[218:221], v[18:21]
	v_mfma_f32_16x16x32_bf16 v[6:9], v[174:177], v[226:229], v[6:9]
	v_mfma_f32_16x16x32_bf16 v[2:5], v[182:185], v[226:229], v[2:5]
	s_setprio 0
	s_barrier
	s_add_i32 s65, s65, 2
	s_add_u32 s80, s80, 0x100
	s_addc_u32 s81, s81, 0
	s_add_u32 s63, s63, 0x100
	s_addc_u32 s64, s64, 0

.LBB0_1933:
	s_ashr_i32 s59, s58, 31
	s_lshl_b64 s[14:15], s[58:59], 18
	s_add_u32 s60, s2, s14
	s_addc_u32 s61, s39, s15
	s_and_b64 s[14:15], s[6:7], exec
	s_cselect_b32 s14, s61, s67
	s_cselect_b32 s15, s60, s66
	s_ashr_i32 s57, s56, 31
	s_lshl_b64 s[36:37], s[56:57], 18
	s_add_u32 s62, s90, s36
	s_addc_u32 s63, s91, s37
	s_and_b64 s[36:37], s[6:7], exec
	s_cselect_b32 s33, s63, s69
	s_cselect_b32 s36, s62, s68
	s_add_u32 s66, s66, 0x20080
	s_addc_u32 s67, s67, 0
	s_add_u32 s37, s68, 0x100
	s_addc_u32 s57, s69, 0
	s_mov_b32 s59, -2
	s_waitcnt lgkmcnt(0)
	ds_read_b128 v[130:133], v183
	ds_read_b128 v[134:137], v183 offset:1024
	ds_read_b128 v[138:141], v183 offset:2048
	ds_read_b128 v[142:145], v183 offset:3072
	ds_read_b128 v[146:149], v184
	ds_read_b128 v[150:153], v184 offset:1024
	ds_read_b128 v[176:179], v184 offset:2048
	ds_read_b128 v[188:191], v184 offset:3072
	s_add_u32 s50, s66, 0xfffe0080
	s_addc_u32 s51, s67, -1
	s_cmp_eq_u32 s59, 4
	s_cselect_b32 s71, s14, s51
	s_cselect_b32 s70, s15, s50
	s_cselect_b32 s69, s33, s57
	s_cselect_b32 s68, s36, s37
	v_lshl_add_u64 v[228:229], s[66:67], 0, v[168:169]
	s_add_i32 m0, s21, 0xc000
	ds_read_b128 v[192:195], v185
	ds_read_b128 v[196:199], v185 offset:1024
	ds_read_b128 v[204:207], v185 offset:2048
	ds_read_b128 v[208:211], v185 offset:3072
	ds_read_b128 v[212:215], v185 offset:4096
	ds_read_b128 v[216:219], v185 offset:5120
	ds_read_b128 v[220:223], v185 offset:6144
	ds_read_b128 v[224:227], v185 offset:7168
	global_load_lds_dwordx4 v[228:229], off
	v_lshl_add_u64 v[228:229], s[66:67], 0, v[170:171]
	s_add_i32 m0, s21, 0xe000
	s_nop 0
	global_load_lds_dwordx4 v[228:229], off
	s_waitcnt vmcnt(8)
	s_waitcnt lgkmcnt(0)
	s_barrier
	s_setprio 1
	s_waitcnt lgkmcnt(0)
	v_mfma_f32_16x16x32_bf16 v[126:129], v[130:133], v[192:195], 0
	v_mfma_f32_16x16x32_bf16 v[122:125], v[138:141], v[192:195], 0
	v_mfma_f32_16x16x32_bf16 v[110:113], v[130:133], v[204:207], 0
	v_mfma_f32_16x16x32_bf16 v[106:109], v[138:141], v[204:207], 0
	v_mfma_f32_16x16x32_bf16 v[94:97], v[130:133], v[212:215], 0
	v_mfma_f32_16x16x32_bf16 v[90:93], v[138:141], v[212:215], 0
	v_mfma_f32_16x16x32_bf16 v[78:81], v[130:133], v[220:223], 0
	v_mfma_f32_16x16x32_bf16 v[74:77], v[138:141], v[220:223], 0
	v_mfma_f32_16x16x32_bf16 v[126:129], v[134:137], v[196:199], v[126:129]
	v_mfma_f32_16x16x32_bf16 v[122:125], v[142:145], v[196:199], v[122:125]
	v_mfma_f32_16x16x32_bf16 v[110:113], v[134:137], v[208:211], v[110:113]
	v_mfma_f32_16x16x32_bf16 v[106:109], v[142:145], v[208:211], v[106:109]
	v_mfma_f32_16x16x32_bf16 v[94:97], v[134:137], v[216:219], v[94:97]
	v_mfma_f32_16x16x32_bf16 v[90:93], v[142:145], v[216:219], v[90:93]
	v_mfma_f32_16x16x32_bf16 v[78:81], v[134:137], v[224:227], v[78:81]
	v_mfma_f32_16x16x32_bf16 v[74:77], v[142:145], v[224:227], v[74:77]
	s_setprio 0
	s_setprio 1
	v_mfma_f32_16x16x32_bf16 v[118:121], v[146:149], v[192:195], 0
	v_mfma_f32_16x16x32_bf16 v[114:117], v[176:179], v[192:195], 0
	v_mfma_f32_16x16x32_bf16 v[102:105], v[146:149], v[204:207], 0
	v_mfma_f32_16x16x32_bf16 v[98:101], v[176:179], v[204:207], 0
	v_mfma_f32_16x16x32_bf16 v[86:89], v[146:149], v[212:215], 0
	v_mfma_f32_16x16x32_bf16 v[82:85], v[176:179], v[212:215], 0
	v_mfma_f32_16x16x32_bf16 v[70:73], v[146:149], v[220:223], 0
	v_mfma_f32_16x16x32_bf16 v[66:69], v[176:179], v[220:223], 0
	v_mfma_f32_16x16x32_bf16 v[118:121], v[150:153], v[196:199], v[118:121]
	v_mfma_f32_16x16x32_bf16 v[114:117], v[188:191], v[196:199], v[114:117]
	v_mfma_f32_16x16x32_bf16 v[102:105], v[150:153], v[208:211], v[102:105]
	v_mfma_f32_16x16x32_bf16 v[98:101], v[188:191], v[208:211], v[98:101]
	v_mfma_f32_16x16x32_bf16 v[86:89], v[150:153], v[216:219], v[86:89]
	v_mfma_f32_16x16x32_bf16 v[82:85], v[188:191], v[216:219], v[82:85]
	v_mfma_f32_16x16x32_bf16 v[70:73], v[150:153], v[224:227], v[70:73]
	v_mfma_f32_16x16x32_bf16 v[66:69], v[188:191], v[224:227], v[66:69]
	s_setprio 0
	s_barrier
	s_add_i32 s50, s76, s20
	v_lshl_add_u64 v[228:229], s[68:69], 0, v[156:157]
	s_mov_b32 m0, s50
	ds_read_b128 v[192:195], v185 offset:16384
	ds_read_b128 v[196:199], v185 offset:17408
	ds_read_b128 v[204:207], v185 offset:18432
	ds_read_b128 v[208:211], v185 offset:19456
	ds_read_b128 v[212:215], v185 offset:20480
	ds_read_b128 v[216:219], v185 offset:21504
	ds_read_b128 v[220:223], v185 offset:22528
	ds_read_b128 v[224:227], v185 offset:23552
	global_load_lds_dwordx4 v[228:229], off
	s_add_i32 m0, s50, 0x2000
	s_add_u32 s50, s68, 0x20000
	v_lshl_add_u64 v[230:231], s[68:69], 0, v[160:161]
	s_addc_u32 s51, s69, 0
	s_add_i32 s79, s77, s20
	global_load_lds_dwordx4 v[230:231], off
	v_lshl_add_u64 v[232:233], s[50:51], 0, v[156:157]
	s_mov_b32 m0, s79
	v_lshl_add_u64 v[234:235], s[70:71], 0, v[158:159]
	global_load_lds_dwordx4 v[232:233], off
	v_lshl_add_u64 v[232:233], s[50:51], 0, v[160:161]
	s_add_i32 m0, s79, 0x2000
	s_nop 0
	global_load_lds_dwordx4 v[232:233], off
	v_lshl_add_u64 v[232:233], s[70:71], 0, v[154:155]
	s_mov_b32 m0, s21
	s_nop 0
	global_load_lds_dwordx4 v[232:233], off
	s_mov_b32 m0, s23
	s_nop 0
	global_load_lds_dwordx4 v[234:235], off
	s_waitcnt vmcnt(8)
	s_waitcnt lgkmcnt(0)
	s_barrier
	s_setprio 1
	s_waitcnt lgkmcnt(0)
	v_mfma_f32_16x16x32_bf16 v[62:65], v[130:133], v[192:195], 0
	v_mfma_f32_16x16x32_bf16 v[58:61], v[138:141], v[192:195], 0
	v_mfma_f32_16x16x32_bf16 v[46:49], v[130:133], v[204:207], 0
	v_mfma_f32_16x16x32_bf16 v[42:45], v[138:141], v[204:207], 0
	v_mfma_f32_16x16x32_bf16 v[30:33], v[130:133], v[212:215], 0
	v_mfma_f32_16x16x32_bf16 v[26:29], v[138:141], v[212:215], 0
	v_mfma_f32_16x16x32_bf16 v[14:17], v[130:133], v[220:223], 0
	v_mfma_f32_16x16x32_bf16 v[10:13], v[138:141], v[220:223], 0
	v_mfma_f32_16x16x32_bf16 v[62:65], v[134:137], v[196:199], v[62:65]
	v_mfma_f32_16x16x32_bf16 v[58:61], v[142:145], v[196:199], v[58:61]
	v_mfma_f32_16x16x32_bf16 v[46:49], v[134:137], v[208:211], v[46:49]
	v_mfma_f32_16x16x32_bf16 v[42:45], v[142:145], v[208:211], v[42:45]
	v_mfma_f32_16x16x32_bf16 v[30:33], v[134:137], v[216:219], v[30:33]
	v_mfma_f32_16x16x32_bf16 v[26:29], v[142:145], v[216:219], v[26:29]
	v_mfma_f32_16x16x32_bf16 v[14:17], v[134:137], v[224:227], v[14:17]
	v_mfma_f32_16x16x32_bf16 v[10:13], v[142:145], v[224:227], v[10:13]
	s_setprio 0
	s_setprio 1
	v_mfma_f32_16x16x32_bf16 v[54:57], v[146:149], v[192:195], 0
	v_mfma_f32_16x16x32_bf16 v[50:53], v[176:179], v[192:195], 0
	v_mfma_f32_16x16x32_bf16 v[38:41], v[146:149], v[204:207], 0
	v_mfma_f32_16x16x32_bf16 v[34:37], v[176:179], v[204:207], 0
	v_mfma_f32_16x16x32_bf16 v[22:25], v[146:149], v[212:215], 0
	v_mfma_f32_16x16x32_bf16 v[18:21], v[176:179], v[212:215], 0
	v_mfma_f32_16x16x32_bf16 v[6:9], v[146:149], v[220:223], 0
	v_mfma_f32_16x16x32_bf16 v[2:5], v[176:179], v[220:223], 0
	v_mfma_f32_16x16x32_bf16 v[54:57], v[150:153], v[196:199], v[54:57]
	v_mfma_f32_16x16x32_bf16 v[50:53], v[188:191], v[196:199], v[50:53]
	v_mfma_f32_16x16x32_bf16 v[38:41], v[150:153], v[208:211], v[38:41]
	v_mfma_f32_16x16x32_bf16 v[34:37], v[188:191], v[208:211], v[34:37]
	v_mfma_f32_16x16x32_bf16 v[22:25], v[150:153], v[216:219], v[22:25]
	v_mfma_f32_16x16x32_bf16 v[18:21], v[188:191], v[216:219], v[18:21]
	v_mfma_f32_16x16x32_bf16 v[6:9], v[150:153], v[224:227], v[6:9]
	v_mfma_f32_16x16x32_bf16 v[2:5], v[188:191], v[224:227], v[2:5]
	s_setprio 0
	s_barrier
	s_add_i32 s79, 0, 0x18000
	s_add_i32 s80, 0, 0x1c000
	v_add_u32_e32 v142, s79, v181
	v_add_u32_e32 v166, s80, v181
	ds_read_b128 v[130:133], v142
	ds_read_b128 v[134:137], v142 offset:1024
	ds_read_b128 v[138:141], v142 offset:2048
	ds_read_b128 v[142:145], v142 offset:3072
	ds_read_b128 v[146:149], v166
	ds_read_b128 v[150:153], v166 offset:1024
	ds_read_b128 v[176:179], v166 offset:2048
	ds_read_b128 v[188:191], v166 offset:3072
	s_add_u32 s50, s70, 0x20000
	s_addc_u32 s51, s71, 0
	s_mov_b32 m0, s26
	v_lshl_add_u64 v[236:237], s[50:51], 0, v[154:155]
	ds_read_b128 v[192:195], v185 offset:32768
	ds_read_b128 v[196:199], v185 offset:33792
	ds_read_b128 v[204:207], v185 offset:34816
	ds_read_b128 v[208:211], v185 offset:35840
	ds_read_b128 v[212:215], v185 offset:36864
	ds_read_b128 v[216:219], v185 offset:37888
	ds_read_b128 v[220:223], v185 offset:38912
	ds_read_b128 v[224:227], v185 offset:39936
	global_load_lds_dwordx4 v[236:237], off
	v_lshl_add_u64 v[236:237], s[50:51], 0, v[158:159]
	s_mov_b32 m0, s27
	s_nop 0
	global_load_lds_dwordx4 v[236:237], off
	s_waitcnt vmcnt(8)
	s_waitcnt lgkmcnt(0)
	s_barrier
	s_setprio 1
	s_waitcnt lgkmcnt(0)
	v_mfma_f32_16x16x32_bf16 v[126:129], v[130:133], v[192:195], v[126:129]
	v_mfma_f32_16x16x32_bf16 v[122:125], v[138:141], v[192:195], v[122:125]
	v_mfma_f32_16x16x32_bf16 v[110:113], v[130:133], v[204:207], v[110:113]
	v_mfma_f32_16x16x32_bf16 v[106:109], v[138:141], v[204:207], v[106:109]
	v_mfma_f32_16x16x32_bf16 v[94:97], v[130:133], v[212:215], v[94:97]
	v_mfma_f32_16x16x32_bf16 v[90:93], v[138:141], v[212:215], v[90:93]
	v_mfma_f32_16x16x32_bf16 v[78:81], v[130:133], v[220:223], v[78:81]
	v_mfma_f32_16x16x32_bf16 v[74:77], v[138:141], v[220:223], v[74:77]
	v_mfma_f32_16x16x32_bf16 v[126:129], v[134:137], v[196:199], v[126:129]
	v_mfma_f32_16x16x32_bf16 v[122:125], v[142:145], v[196:199], v[122:125]
	v_mfma_f32_16x16x32_bf16 v[110:113], v[134:137], v[208:211], v[110:113]
	v_mfma_f32_16x16x32_bf16 v[106:109], v[142:145], v[208:211], v[106:109]
	v_mfma_f32_16x16x32_bf16 v[94:97], v[134:137], v[216:219], v[94:97]
	v_mfma_f32_16x16x32_bf16 v[90:93], v[142:145], v[216:219], v[90:93]
	v_mfma_f32_16x16x32_bf16 v[78:81], v[134:137], v[224:227], v[78:81]
	v_mfma_f32_16x16x32_bf16 v[74:77], v[142:145], v[224:227], v[74:77]
	s_setprio 0
	s_setprio 1
	v_mfma_f32_16x16x32_bf16 v[118:121], v[146:149], v[192:195], v[118:121]
	v_mfma_f32_16x16x32_bf16 v[114:117], v[176:179], v[192:195], v[114:117]
	v_mfma_f32_16x16x32_bf16 v[102:105], v[146:149], v[204:207], v[102:105]
	v_mfma_f32_16x16x32_bf16 v[98:101], v[176:179], v[204:207], v[98:101]
	v_mfma_f32_16x16x32_bf16 v[86:89], v[146:149], v[212:215], v[86:89]
	v_mfma_f32_16x16x32_bf16 v[82:85], v[176:179], v[212:215], v[82:85]
	v_mfma_f32_16x16x32_bf16 v[70:73], v[146:149], v[220:223], v[70:73]
	v_mfma_f32_16x16x32_bf16 v[66:69], v[176:179], v[220:223], v[66:69]
	v_mfma_f32_16x16x32_bf16 v[118:121], v[150:153], v[196:199], v[118:121]
	v_mfma_f32_16x16x32_bf16 v[114:117], v[188:191], v[196:199], v[114:117]
	v_mfma_f32_16x16x32_bf16 v[102:105], v[150:153], v[208:211], v[102:105]
	v_mfma_f32_16x16x32_bf16 v[98:101], v[188:191], v[208:211], v[98:101]
	v_mfma_f32_16x16x32_bf16 v[86:89], v[150:153], v[216:219], v[86:89]
	v_mfma_f32_16x16x32_bf16 v[82:85], v[188:191], v[216:219], v[82:85]
	v_mfma_f32_16x16x32_bf16 v[70:73], v[150:153], v[224:227], v[70:73]
	v_mfma_f32_16x16x32_bf16 v[66:69], v[188:191], v[224:227], v[66:69]
	s_setprio 0
	s_barrier
	s_add_i32 s50, s79, s20
	v_lshl_add_u64 v[228:229], v[228:229], 0, s[52:53]
	s_mov_b32 m0, s50
	ds_read_b128 v[192:195], v185 offset:49152
	ds_read_b128 v[196:199], v185 offset:50176
	ds_read_b128 v[204:207], v185 offset:51200
	ds_read_b128 v[208:211], v185 offset:52224
	ds_read_b128 v[212:215], v185 offset:53248
	ds_read_b128 v[216:219], v185 offset:54272
	ds_read_b128 v[220:223], v185 offset:55296
	ds_read_b128 v[224:227], v185 offset:56320
	global_load_lds_dwordx4 v[228:229], off
	s_add_i32 m0, s50, 0x2000
	s_add_u32 s50, s68, 0x20080
	v_lshl_add_u64 v[228:229], v[230:231], 0, s[52:53]
	s_addc_u32 s51, s69, 0
	s_add_i32 s68, s80, s20
	global_load_lds_dwordx4 v[228:229], off
	v_lshl_add_u64 v[228:229], s[50:51], 0, v[156:157]
	s_mov_b32 m0, s68
	s_nop 0
	global_load_lds_dwordx4 v[228:229], off
	v_lshl_add_u64 v[228:229], s[50:51], 0, v[160:161]
	s_add_i32 m0, s68, 0x2000
	s_nop 0
	global_load_lds_dwordx4 v[228:229], off
	v_lshl_add_u64 v[228:229], v[232:233], 0, s[52:53]
	s_mov_b32 m0, s65
	s_nop 0
	global_load_lds_dwordx4 v[228:229], off
	v_lshl_add_u64 v[228:229], v[234:235], 0, s[52:53]
	s_mov_b32 m0, s72
	s_nop 0
	global_load_lds_dwordx4 v[228:229], off
	s_waitcnt vmcnt(8)
	s_waitcnt lgkmcnt(0)
	s_barrier
	s_setprio 1
	s_waitcnt lgkmcnt(0)
	v_mfma_f32_16x16x32_bf16 v[62:65], v[130:133], v[192:195], v[62:65]
	v_mfma_f32_16x16x32_bf16 v[58:61], v[138:141], v[192:195], v[58:61]
	v_mfma_f32_16x16x32_bf16 v[46:49], v[130:133], v[204:207], v[46:49]
	v_mfma_f32_16x16x32_bf16 v[42:45], v[138:141], v[204:207], v[42:45]
	v_mfma_f32_16x16x32_bf16 v[30:33], v[130:133], v[212:215], v[30:33]
	v_mfma_f32_16x16x32_bf16 v[26:29], v[138:141], v[212:215], v[26:29]
	v_mfma_f32_16x16x32_bf16 v[14:17], v[130:133], v[220:223], v[14:17]
	v_mfma_f32_16x16x32_bf16 v[10:13], v[138:141], v[220:223], v[10:13]
	v_mfma_f32_16x16x32_bf16 v[62:65], v[134:137], v[196:199], v[62:65]
	v_mfma_f32_16x16x32_bf16 v[58:61], v[142:145], v[196:199], v[58:61]
	v_mfma_f32_16x16x32_bf16 v[46:49], v[134:137], v[208:211], v[46:49]
	v_mfma_f32_16x16x32_bf16 v[42:45], v[142:145], v[208:211], v[42:45]
	v_mfma_f32_16x16x32_bf16 v[30:33], v[134:137], v[216:219], v[30:33]
	v_mfma_f32_16x16x32_bf16 v[26:29], v[142:145], v[216:219], v[26:29]
	v_mfma_f32_16x16x32_bf16 v[14:17], v[134:137], v[224:227], v[14:17]
	v_mfma_f32_16x16x32_bf16 v[10:13], v[142:145], v[224:227], v[10:13]
	s_setprio 0
	s_setprio 1
	v_mfma_f32_16x16x32_bf16 v[54:57], v[146:149], v[192:195], v[54:57]
	v_mfma_f32_16x16x32_bf16 v[50:53], v[176:179], v[192:195], v[50:53]
	v_mfma_f32_16x16x32_bf16 v[38:41], v[146:149], v[204:207], v[38:41]
	v_mfma_f32_16x16x32_bf16 v[34:37], v[176:179], v[204:207], v[34:37]
	v_mfma_f32_16x16x32_bf16 v[22:25], v[146:149], v[212:215], v[22:25]
	v_mfma_f32_16x16x32_bf16 v[18:21], v[176:179], v[212:215], v[18:21]
	v_mfma_f32_16x16x32_bf16 v[6:9], v[146:149], v[220:223], v[6:9]
	v_mfma_f32_16x16x32_bf16 v[2:5], v[176:179], v[220:223], v[2:5]
	v_mfma_f32_16x16x32_bf16 v[54:57], v[150:153], v[196:199], v[54:57]
	v_mfma_f32_16x16x32_bf16 v[50:53], v[188:191], v[196:199], v[50:53]
	v_mfma_f32_16x16x32_bf16 v[38:41], v[150:153], v[208:211], v[38:41]
	v_mfma_f32_16x16x32_bf16 v[34:37], v[188:191], v[208:211], v[34:37]
	v_mfma_f32_16x16x32_bf16 v[22:25], v[150:153], v[216:219], v[22:25]
	v_mfma_f32_16x16x32_bf16 v[18:21], v[188:191], v[216:219], v[18:21]
	v_mfma_f32_16x16x32_bf16 v[6:9], v[150:153], v[224:227], v[6:9]
	v_mfma_f32_16x16x32_bf16 v[2:5], v[188:191], v[224:227], v[2:5]
	s_setprio 0
	s_barrier
	s_add_i32 s59, s59, 2
	s_add_u32 s66, s66, 0x100
	s_addc_u32 s67, s67, 0
	s_add_u32 s37, s37, 0x100
	s_addc_u32 s57, s57, 0

.LBB0_2170:
	s_ashr_i32 s49, s48, 31
	s_lshl_b64 s[50:51], s[48:49], 20
	s_add_u32 s50, s21, s50
	s_addc_u32 s51, s26, s51
	s_and_b64 s[52:53], s[4:5], exec
	s_cselect_b32 s49, s51, s57
	s_cselect_b32 s68, s50, s56
	s_ashr_i32 s31, s30, 31
	s_lshl_b64 s[52:53], s[30:31], 20
	s_add_u32 s52, s42, s52
	s_addc_u32 s53, s43, s53
	s_and_b64 s[60:61], s[4:5], exec
	s_cselect_b32 s31, s53, s59
	s_cselect_b32 s69, s52, s58
	s_add_u32 s56, s56, 0x80080
	s_addc_u32 s57, s57, 0
	s_add_u32 s70, s58, 0x100
	s_addc_u32 s71, s59, 0
	s_mov_b32 s72, -2
	ds_read_b128 v[18:21], v193
	ds_read_b128 v[22:25], v193 offset:1024
	ds_read_b128 v[26:29], v193 offset:2048
	ds_read_b128 v[30:33], v193 offset:3072
	ds_read_b128 v[2:5], v194
	ds_read_b128 v[6:9], v194 offset:1024
	ds_read_b128 v[10:13], v194 offset:2048
	ds_read_b128 v[14:17], v194 offset:3072
	s_add_u32 s58, s56, 0xfff80080
	s_addc_u32 s59, s57, -1
	s_cmp_eq_u32 s72, 28
	s_cselect_b32 s61, s49, s59
	s_cselect_b32 s60, s68, s58
	s_cselect_b32 s59, s31, s71
	s_cselect_b32 s58, s69, s70
	v_lshl_add_u64 v[198:199], s[56:57], 0, v[174:175]
	s_add_i32 m0, s37, 0xc000
	ds_read_b128 v[182:185], v195
	ds_read_b128 v[186:189], v195 offset:1024
	ds_read_b128 v[204:207], v195 offset:2048
	ds_read_b128 v[208:211], v195 offset:3072
	ds_read_b128 v[212:215], v195 offset:4096
	ds_read_b128 v[216:219], v195 offset:5120
	ds_read_b128 v[220:223], v195 offset:6144
	ds_read_b128 v[224:227], v195 offset:7168
	global_load_lds_dwordx4 v[198:199], off
	v_lshl_add_u64 v[198:199], s[56:57], 0, v[176:177]
	s_add_i32 m0, s37, 0xe000
	s_nop 0
	global_load_lds_dwordx4 v[198:199], off
	s_waitcnt vmcnt(8)
	s_waitcnt lgkmcnt(0)
	s_barrier
	s_setprio 1
	s_waitcnt lgkmcnt(0)
	v_mfma_scale_f32_16x16x128_f8f6f4 v[158:161], v[18:25], v[182:189], 0, v196, v196 op_sel_hi:[0,0,0]
	v_mfma_scale_f32_16x16x128_f8f6f4 v[154:157], v[26:33], v[182:189], 0, v196, v196 op_sel_hi:[0,0,0]
	v_mfma_scale_f32_16x16x128_f8f6f4 v[142:145], v[18:25], v[204:211], 0, v196, v196 op_sel_hi:[0,0,0]
	v_mfma_scale_f32_16x16x128_f8f6f4 v[138:141], v[26:33], v[204:211], 0, v196, v196 op_sel_hi:[0,0,0]
	v_mfma_scale_f32_16x16x128_f8f6f4 v[126:129], v[18:25], v[212:219], 0, v196, v196 op_sel_hi:[0,0,0]
	v_mfma_scale_f32_16x16x128_f8f6f4 v[122:125], v[26:33], v[212:219], 0, v196, v196 op_sel_hi:[0,0,0]
	v_mfma_scale_f32_16x16x128_f8f6f4 v[110:113], v[18:25], v[220:227], 0, v196, v196 op_sel_hi:[0,0,0]
	v_mfma_scale_f32_16x16x128_f8f6f4 v[106:109], v[26:33], v[220:227], 0, v196, v196 op_sel_hi:[0,0,0]
	s_setprio 0
	s_setprio 1
	v_mfma_scale_f32_16x16x128_f8f6f4 v[150:153], v[2:9], v[182:189], 0, v196, v196 op_sel_hi:[0,0,0]
	v_mfma_scale_f32_16x16x128_f8f6f4 v[146:149], v[10:17], v[182:189], 0, v196, v196 op_sel_hi:[0,0,0]
	v_mfma_scale_f32_16x16x128_f8f6f4 v[134:137], v[2:9], v[204:211], 0, v196, v196 op_sel_hi:[0,0,0]
	v_mfma_scale_f32_16x16x128_f8f6f4 v[130:133], v[10:17], v[204:211], 0, v196, v196 op_sel_hi:[0,0,0]
	v_mfma_scale_f32_16x16x128_f8f6f4 v[118:121], v[2:9], v[212:219], 0, v196, v196 op_sel_hi:[0,0,0]
	v_mfma_scale_f32_16x16x128_f8f6f4 v[114:117], v[10:17], v[212:219], 0, v196, v196 op_sel_hi:[0,0,0]
	v_mfma_scale_f32_16x16x128_f8f6f4 v[102:105], v[2:9], v[220:227], 0, v196, v196 op_sel_hi:[0,0,0]
	v_mfma_scale_f32_16x16x128_f8f6f4 v[98:101], v[10:17], v[220:227], 0, v196, v196 op_sel_hi:[0,0,0]
	s_setprio 0
	s_barrier
	s_add_i32 s73, s15, s20
	v_lshl_add_u64 v[182:183], s[58:59], 0, v[170:171]
	s_mov_b32 m0, s73
	ds_read_b128 v[204:207], v195 offset:16384
	ds_read_b128 v[208:211], v195 offset:17408
	ds_read_b128 v[212:215], v195 offset:18432
	ds_read_b128 v[216:219], v195 offset:19456
	ds_read_b128 v[220:223], v195 offset:20480
	ds_read_b128 v[224:227], v195 offset:21504
	ds_read_b128 v[228:231], v195 offset:22528
	ds_read_b128 v[232:235], v195 offset:23552
	global_load_lds_dwordx4 v[182:183], off
	s_add_i32 m0, s73, 0x2000
	s_add_u32 s74, s58, 0x80000
	v_lshl_add_u64 v[184:185], s[58:59], 0, v[166:167]
	s_addc_u32 s75, s59, 0
	s_add_i32 s73, s65, s20
	global_load_lds_dwordx4 v[184:185], off
	v_lshl_add_u64 v[186:187], s[74:75], 0, v[170:171]
	s_mov_b32 m0, s73
	v_lshl_add_u64 v[188:189], s[60:61], 0, v[168:169]
	global_load_lds_dwordx4 v[186:187], off
	v_lshl_add_u64 v[186:187], s[74:75], 0, v[166:167]
	s_add_i32 m0, s73, 0x2000
	s_nop 0
	global_load_lds_dwordx4 v[186:187], off
	v_lshl_add_u64 v[186:187], s[60:61], 0, v[172:173]
	s_mov_b32 m0, s37
	s_nop 0
	global_load_lds_dwordx4 v[186:187], off
	s_mov_b32 m0, s38
	s_nop 0
	global_load_lds_dwordx4 v[188:189], off
	s_waitcnt vmcnt(8)
	s_waitcnt lgkmcnt(0)
	s_barrier
	s_setprio 1
	s_waitcnt lgkmcnt(0)
	v_mfma_scale_f32_16x16x128_f8f6f4 v[94:97], v[18:25], v[204:211], 0, v196, v196 op_sel_hi:[0,0,0]
	v_mfma_scale_f32_16x16x128_f8f6f4 v[90:93], v[26:33], v[204:211], 0, v196, v196 op_sel_hi:[0,0,0]
	v_mfma_scale_f32_16x16x128_f8f6f4 v[78:81], v[18:25], v[212:219], 0, v196, v196 op_sel_hi:[0,0,0]
	v_mfma_scale_f32_16x16x128_f8f6f4 v[74:77], v[26:33], v[212:219], 0, v196, v196 op_sel_hi:[0,0,0]
	v_mfma_scale_f32_16x16x128_f8f6f4 v[62:65], v[18:25], v[220:227], 0, v196, v196 op_sel_hi:[0,0,0]
	v_mfma_scale_f32_16x16x128_f8f6f4 v[58:61], v[26:33], v[220:227], 0, v196, v196 op_sel_hi:[0,0,0]
	v_mfma_scale_f32_16x16x128_f8f6f4 v[46:49], v[18:25], v[228:235], 0, v196, v196 op_sel_hi:[0,0,0]
	v_mfma_scale_f32_16x16x128_f8f6f4 v[42:45], v[26:33], v[228:235], 0, v196, v196 op_sel_hi:[0,0,0]
	s_setprio 0
	s_setprio 1
	v_mfma_scale_f32_16x16x128_f8f6f4 v[86:89], v[2:9], v[204:211], 0, v196, v196 op_sel_hi:[0,0,0]
	v_mfma_scale_f32_16x16x128_f8f6f4 v[82:85], v[10:17], v[204:211], 0, v196, v196 op_sel_hi:[0,0,0]
	v_mfma_scale_f32_16x16x128_f8f6f4 v[70:73], v[2:9], v[212:219], 0, v196, v196 op_sel_hi:[0,0,0]
	v_mfma_scale_f32_16x16x128_f8f6f4 v[66:69], v[10:17], v[212:219], 0, v196, v196 op_sel_hi:[0,0,0]
	v_mfma_scale_f32_16x16x128_f8f6f4 v[54:57], v[2:9], v[220:227], 0, v196, v196 op_sel_hi:[0,0,0]
	v_mfma_scale_f32_16x16x128_f8f6f4 v[50:53], v[10:17], v[220:227], 0, v196, v196 op_sel_hi:[0,0,0]
	v_mfma_scale_f32_16x16x128_f8f6f4 v[38:41], v[2:9], v[228:235], 0, v196, v196 op_sel_hi:[0,0,0]
	v_mfma_scale_f32_16x16x128_f8f6f4 v[34:37], v[10:17], v[228:235], 0, v196, v196 op_sel_hi:[0,0,0]
	s_setprio 0
	s_barrier
	s_add_i32 s73, 0, 0x18000
	s_add_i32 s74, 0, 0x1c000
	v_add_u32_e32 v14, s73, v191
	v_add_u32_e32 v30, s74, v191
	ds_read_b128 v[2:5], v14
	ds_read_b128 v[6:9], v14 offset:1024
	ds_read_b128 v[10:13], v14 offset:2048
	ds_read_b128 v[14:17], v14 offset:3072
	ds_read_b128 v[18:21], v30
	ds_read_b128 v[22:25], v30 offset:1024
	ds_read_b128 v[26:29], v30 offset:2048
	ds_read_b128 v[30:33], v30 offset:3072
	s_add_u32 s60, s60, 0x80000
	s_addc_u32 s61, s61, 0
	s_mov_b32 m0, s39
	v_lshl_add_u64 v[198:199], s[60:61], 0, v[172:173]
	ds_read_b128 v[204:207], v195 offset:32768
	ds_read_b128 v[208:211], v195 offset:33792
	ds_read_b128 v[212:215], v195 offset:34816
	ds_read_b128 v[216:219], v195 offset:35840
	ds_read_b128 v[220:223], v195 offset:36864
	ds_read_b128 v[224:227], v195 offset:37888
	ds_read_b128 v[228:231], v195 offset:38912
	ds_read_b128 v[232:235], v195 offset:39936
	global_load_lds_dwordx4 v[198:199], off
	v_lshl_add_u64 v[198:199], s[60:61], 0, v[168:169]
	s_mov_b32 m0, s55
	s_nop 0
	global_load_lds_dwordx4 v[198:199], off
	s_waitcnt vmcnt(8)
	s_waitcnt lgkmcnt(0)
	s_barrier
	s_setprio 1
	s_waitcnt lgkmcnt(0)
	v_mfma_scale_f32_16x16x128_f8f6f4 v[158:161], v[2:9], v[204:211], v[158:161], v196, v196 op_sel_hi:[0,0,0]
	v_mfma_scale_f32_16x16x128_f8f6f4 v[154:157], v[10:17], v[204:211], v[154:157], v196, v196 op_sel_hi:[0,0,0]
	v_mfma_scale_f32_16x16x128_f8f6f4 v[142:145], v[2:9], v[212:219], v[142:145], v196, v196 op_sel_hi:[0,0,0]
	v_mfma_scale_f32_16x16x128_f8f6f4 v[138:141], v[10:17], v[212:219], v[138:141], v196, v196 op_sel_hi:[0,0,0]
	v_mfma_scale_f32_16x16x128_f8f6f4 v[126:129], v[2:9], v[220:227], v[126:129], v196, v196 op_sel_hi:[0,0,0]
	v_mfma_scale_f32_16x16x128_f8f6f4 v[122:125], v[10:17], v[220:227], v[122:125], v196, v196 op_sel_hi:[0,0,0]
	v_mfma_scale_f32_16x16x128_f8f6f4 v[110:113], v[2:9], v[228:235], v[110:113], v196, v196 op_sel_hi:[0,0,0]
	v_mfma_scale_f32_16x16x128_f8f6f4 v[106:109], v[10:17], v[228:235], v[106:109], v196, v196 op_sel_hi:[0,0,0]
	s_setprio 0
	s_setprio 1
	v_mfma_scale_f32_16x16x128_f8f6f4 v[150:153], v[18:25], v[204:211], v[150:153], v196, v196 op_sel_hi:[0,0,0]
	v_mfma_scale_f32_16x16x128_f8f6f4 v[146:149], v[26:33], v[204:211], v[146:149], v196, v196 op_sel_hi:[0,0,0]
	v_mfma_scale_f32_16x16x128_f8f6f4 v[134:137], v[18:25], v[212:219], v[134:137], v196, v196 op_sel_hi:[0,0,0]
	v_mfma_scale_f32_16x16x128_f8f6f4 v[130:133], v[26:33], v[212:219], v[130:133], v196, v196 op_sel_hi:[0,0,0]
	v_mfma_scale_f32_16x16x128_f8f6f4 v[118:121], v[18:25], v[220:227], v[118:121], v196, v196 op_sel_hi:[0,0,0]
	v_mfma_scale_f32_16x16x128_f8f6f4 v[114:117], v[26:33], v[220:227], v[114:117], v196, v196 op_sel_hi:[0,0,0]
	v_mfma_scale_f32_16x16x128_f8f6f4 v[102:105], v[18:25], v[228:235], v[102:105], v196, v196 op_sel_hi:[0,0,0]
	v_mfma_scale_f32_16x16x128_f8f6f4 v[98:101], v[26:33], v[228:235], v[98:101], v196, v196 op_sel_hi:[0,0,0]
	s_setprio 0
	s_barrier
	s_add_i32 s60, s73, s20
	v_lshl_add_u64 v[182:183], v[182:183], 0, s[22:23]
	s_mov_b32 m0, s60
	ds_read_b128 v[204:207], v195 offset:49152
	ds_read_b128 v[208:211], v195 offset:50176
	ds_read_b128 v[212:215], v195 offset:51200
	ds_read_b128 v[216:219], v195 offset:52224
	ds_read_b128 v[220:223], v195 offset:53248
	ds_read_b128 v[224:227], v195 offset:54272
	ds_read_b128 v[228:231], v195 offset:55296
	ds_read_b128 v[232:235], v195 offset:56320
	global_load_lds_dwordx4 v[182:183], off
	s_add_i32 m0, s60, 0x2000
	s_add_u32 s58, s58, 0x80080
	v_lshl_add_u64 v[182:183], v[184:185], 0, s[22:23]
	s_addc_u32 s59, s59, 0
	s_add_i32 s60, s74, s20
	global_load_lds_dwordx4 v[182:183], off
	v_lshl_add_u64 v[182:183], s[58:59], 0, v[170:171]
	s_mov_b32 m0, s60
	s_nop 0
	global_load_lds_dwordx4 v[182:183], off
	v_lshl_add_u64 v[182:183], s[58:59], 0, v[166:167]
	s_add_i32 m0, s60, 0x2000
	s_nop 0
	global_load_lds_dwordx4 v[182:183], off
	v_lshl_add_u64 v[182:183], v[186:187], 0, s[22:23]
	s_mov_b32 m0, s63
	s_nop 0
	global_load_lds_dwordx4 v[182:183], off
	v_lshl_add_u64 v[182:183], v[188:189], 0, s[22:23]
	s_mov_b32 m0, s64
	s_nop 0
	global_load_lds_dwordx4 v[182:183], off
	s_waitcnt vmcnt(8)
	s_waitcnt lgkmcnt(0)
	s_barrier
	s_setprio 1
	s_waitcnt lgkmcnt(0)
	v_mfma_scale_f32_16x16x128_f8f6f4 v[94:97], v[2:9], v[204:211], v[94:97], v196, v196 op_sel_hi:[0,0,0]
	v_mfma_scale_f32_16x16x128_f8f6f4 v[90:93], v[10:17], v[204:211], v[90:93], v196, v196 op_sel_hi:[0,0,0]
	v_mfma_scale_f32_16x16x128_f8f6f4 v[78:81], v[2:9], v[212:219], v[78:81], v196, v196 op_sel_hi:[0,0,0]
	v_mfma_scale_f32_16x16x128_f8f6f4 v[74:77], v[10:17], v[212:219], v[74:77], v196, v196 op_sel_hi:[0,0,0]
	v_mfma_scale_f32_16x16x128_f8f6f4 v[62:65], v[2:9], v[220:227], v[62:65], v196, v196 op_sel_hi:[0,0,0]
	v_mfma_scale_f32_16x16x128_f8f6f4 v[58:61], v[10:17], v[220:227], v[58:61], v196, v196 op_sel_hi:[0,0,0]
	v_mfma_scale_f32_16x16x128_f8f6f4 v[46:49], v[2:9], v[228:235], v[46:49], v196, v196 op_sel_hi:[0,0,0]
	v_mfma_scale_f32_16x16x128_f8f6f4 v[42:45], v[10:17], v[228:235], v[42:45], v196, v196 op_sel_hi:[0,0,0]
	s_setprio 0
	s_setprio 1
	v_mfma_scale_f32_16x16x128_f8f6f4 v[86:89], v[18:25], v[204:211], v[86:89], v196, v196 op_sel_hi:[0,0,0]
	v_mfma_scale_f32_16x16x128_f8f6f4 v[82:85], v[26:33], v[204:211], v[82:85], v196, v196 op_sel_hi:[0,0,0]
	v_mfma_scale_f32_16x16x128_f8f6f4 v[70:73], v[18:25], v[212:219], v[70:73], v196, v196 op_sel_hi:[0,0,0]
	v_mfma_scale_f32_16x16x128_f8f6f4 v[66:69], v[26:33], v[212:219], v[66:69], v196, v196 op_sel_hi:[0,0,0]
	v_mfma_scale_f32_16x16x128_f8f6f4 v[54:57], v[18:25], v[220:227], v[54:57], v196, v196 op_sel_hi:[0,0,0]
	v_mfma_scale_f32_16x16x128_f8f6f4 v[50:53], v[26:33], v[220:227], v[50:53], v196, v196 op_sel_hi:[0,0,0]
	v_mfma_scale_f32_16x16x128_f8f6f4 v[38:41], v[18:25], v[228:235], v[38:41], v196, v196 op_sel_hi:[0,0,0]
	v_mfma_scale_f32_16x16x128_f8f6f4 v[34:37], v[26:33], v[228:235], v[34:37], v196, v196 op_sel_hi:[0,0,0]
	s_setprio 0
	s_barrier
	s_add_i32 s72, s72, 2
	s_add_u32 s56, s56, 0x100
	s_addc_u32 s57, s57, 0
	s_add_u32 s70, s70, 0x100
	s_addc_u32 s71, s71, 0

.LBB0_2399:
	s_add_u32 s20, s20, 0x158080
	s_addc_u32 s21, s21, 0
	s_add_u32 s41, s22, 0x100
	s_addc_u32 s42, s23, 0
	s_mov_b32 s43, -2
	ds_read_b128 v[16:19], v187
	ds_read_b128 v[20:23], v187 offset:1024
	ds_read_b128 v[24:27], v187 offset:2048
	ds_read_b128 v[28:31], v187 offset:3072
	ds_read_b128 v[0:3], v188
	ds_read_b128 v[4:7], v188 offset:1024
	ds_read_b128 v[8:11], v188 offset:2048
	ds_read_b128 v[12:15], v188 offset:3072
	s_add_u32 s22, s20, 0xffea8080
	s_addc_u32 s23, s21, -1
	s_cmpk_eq_i32 s43, 0x52
	s_cselect_b32 s25, s5, s23
	s_cselect_b32 s24, s4, s22
	s_cselect_b32 s23, s19, s42
	s_cselect_b32 s22, s18, s41
	v_lshl_add_u64 v[216:217], s[20:21], 0, v[162:163]
	s_add_i32 m0, s26, 0xc000
	ds_read_b128 v[176:179], v189
	ds_read_b128 v[180:183], v189 offset:1024
	ds_read_b128 v[192:195], v189 offset:2048
	ds_read_b128 v[196:199], v189 offset:3072
	ds_read_b128 v[200:203], v189 offset:4096
	ds_read_b128 v[204:207], v189 offset:5120
	ds_read_b128 v[208:211], v189 offset:6144
	ds_read_b128 v[212:215], v189 offset:7168
	global_load_lds_dwordx4 v[216:217], off
	v_lshl_add_u64 v[216:217], s[20:21], 0, v[170:171]
	s_add_i32 m0, s26, 0xe000
	s_nop 0
	global_load_lds_dwordx4 v[216:217], off
	s_waitcnt vmcnt(8)
	s_waitcnt lgkmcnt(0)
	s_barrier
	s_setprio 1
	s_waitcnt lgkmcnt(0)
	v_mfma_scale_f32_16x16x128_f8f6f4 v[156:159], v[16:23], v[176:183], 0, v190, v190 op_sel_hi:[0,0,0]
	v_mfma_scale_f32_16x16x128_f8f6f4 v[152:155], v[24:31], v[176:183], 0, v190, v190 op_sel_hi:[0,0,0]
	v_mfma_scale_f32_16x16x128_f8f6f4 v[148:151], v[16:23], v[192:199], 0, v190, v190 op_sel_hi:[0,0,0]
	v_mfma_scale_f32_16x16x128_f8f6f4 v[144:147], v[24:31], v[192:199], 0, v190, v190 op_sel_hi:[0,0,0]
	v_mfma_scale_f32_16x16x128_f8f6f4 v[132:135], v[16:23], v[200:207], 0, v190, v190 op_sel_hi:[0,0,0]
	v_mfma_scale_f32_16x16x128_f8f6f4 v[120:123], v[24:31], v[200:207], 0, v190, v190 op_sel_hi:[0,0,0]
	v_mfma_scale_f32_16x16x128_f8f6f4 v[112:115], v[16:23], v[208:215], 0, v190, v190 op_sel_hi:[0,0,0]
	v_mfma_scale_f32_16x16x128_f8f6f4 v[104:107], v[24:31], v[208:215], 0, v190, v190 op_sel_hi:[0,0,0]
	s_setprio 0
	s_setprio 1
	v_mfma_scale_f32_16x16x128_f8f6f4 v[140:143], v[0:7], v[176:183], 0, v190, v190 op_sel_hi:[0,0,0]
	v_mfma_scale_f32_16x16x128_f8f6f4 v[136:139], v[8:15], v[176:183], 0, v190, v190 op_sel_hi:[0,0,0]
	v_mfma_scale_f32_16x16x128_f8f6f4 v[128:131], v[0:7], v[192:199], 0, v190, v190 op_sel_hi:[0,0,0]
	v_mfma_scale_f32_16x16x128_f8f6f4 v[124:127], v[8:15], v[192:199], 0, v190, v190 op_sel_hi:[0,0,0]
	v_mfma_scale_f32_16x16x128_f8f6f4 v[116:119], v[0:7], v[200:207], 0, v190, v190 op_sel_hi:[0,0,0]
	v_mfma_scale_f32_16x16x128_f8f6f4 v[108:111], v[8:15], v[200:207], 0, v190, v190 op_sel_hi:[0,0,0]
	v_mfma_scale_f32_16x16x128_f8f6f4 v[100:103], v[0:7], v[208:215], 0, v190, v190 op_sel_hi:[0,0,0]
	v_mfma_scale_f32_16x16x128_f8f6f4 v[96:99], v[8:15], v[208:215], 0, v190, v190 op_sel_hi:[0,0,0]
	s_setprio 0
	s_barrier
	s_add_i32 s48, s35, s15
	v_lshl_add_u64 v[176:177], s[22:23], 0, v[164:165]
	s_mov_b32 m0, s48
	ds_read_b128 v[192:195], v189 offset:16384
	ds_read_b128 v[196:199], v189 offset:17408
	ds_read_b128 v[200:203], v189 offset:18432
	ds_read_b128 v[204:207], v189 offset:19456
	ds_read_b128 v[208:211], v189 offset:20480
	ds_read_b128 v[212:215], v189 offset:21504
	ds_read_b128 v[216:219], v189 offset:22528
	ds_read_b128 v[220:223], v189 offset:23552
	global_load_lds_dwordx4 v[176:177], off
	s_add_i32 m0, s48, 0x2000
	s_add_u32 s48, s22, 0x158000
	v_lshl_add_u64 v[178:179], s[22:23], 0, v[168:169]
	s_addc_u32 s49, s23, 0
	s_add_i32 s50, s36, s15
	global_load_lds_dwordx4 v[178:179], off
	v_lshl_add_u64 v[180:181], s[48:49], 0, v[164:165]
	s_mov_b32 m0, s50
	v_lshl_add_u64 v[182:183], s[24:25], 0, v[166:167]
	global_load_lds_dwordx4 v[180:181], off
	v_lshl_add_u64 v[180:181], s[48:49], 0, v[168:169]
	s_add_i32 m0, s50, 0x2000
	s_nop 0
	global_load_lds_dwordx4 v[180:181], off
	v_lshl_add_u64 v[180:181], s[24:25], 0, v[160:161]
	s_mov_b32 m0, s26
	s_nop 0
	global_load_lds_dwordx4 v[180:181], off
	s_mov_b32 m0, s27
	s_nop 0
	global_load_lds_dwordx4 v[182:183], off
	s_waitcnt vmcnt(8)
	s_waitcnt lgkmcnt(0)
	s_barrier
	s_setprio 1
	s_waitcnt lgkmcnt(0)
	v_mfma_scale_f32_16x16x128_f8f6f4 v[92:95], v[16:23], v[192:199], 0, v190, v190 op_sel_hi:[0,0,0]
	v_mfma_scale_f32_16x16x128_f8f6f4 v[88:91], v[24:31], v[192:199], 0, v190, v190 op_sel_hi:[0,0,0]
	v_mfma_scale_f32_16x16x128_f8f6f4 v[80:83], v[16:23], v[200:207], 0, v190, v190 op_sel_hi:[0,0,0]
	v_mfma_scale_f32_16x16x128_f8f6f4 v[72:75], v[24:31], v[200:207], 0, v190, v190 op_sel_hi:[0,0,0]
	v_mfma_scale_f32_16x16x128_f8f6f4 v[64:67], v[16:23], v[208:215], 0, v190, v190 op_sel_hi:[0,0,0]
	v_mfma_scale_f32_16x16x128_f8f6f4 v[56:59], v[24:31], v[208:215], 0, v190, v190 op_sel_hi:[0,0,0]
	v_mfma_scale_f32_16x16x128_f8f6f4 v[48:51], v[16:23], v[216:223], 0, v190, v190 op_sel_hi:[0,0,0]
	v_mfma_scale_f32_16x16x128_f8f6f4 v[40:43], v[24:31], v[216:223], 0, v190, v190 op_sel_hi:[0,0,0]
	s_setprio 0
	s_setprio 1
	v_mfma_scale_f32_16x16x128_f8f6f4 v[84:87], v[0:7], v[192:199], 0, v190, v190 op_sel_hi:[0,0,0]
	v_mfma_scale_f32_16x16x128_f8f6f4 v[76:79], v[8:15], v[192:199], 0, v190, v190 op_sel_hi:[0,0,0]
	v_mfma_scale_f32_16x16x128_f8f6f4 v[68:71], v[0:7], v[200:207], 0, v190, v190 op_sel_hi:[0,0,0]
	v_mfma_scale_f32_16x16x128_f8f6f4 v[60:63], v[8:15], v[200:207], 0, v190, v190 op_sel_hi:[0,0,0]
	v_mfma_scale_f32_16x16x128_f8f6f4 v[52:55], v[0:7], v[208:215], 0, v190, v190 op_sel_hi:[0,0,0]
	v_mfma_scale_f32_16x16x128_f8f6f4 v[44:47], v[8:15], v[208:215], 0, v190, v190 op_sel_hi:[0,0,0]
	v_mfma_scale_f32_16x16x128_f8f6f4 v[36:39], v[0:7], v[216:223], 0, v190, v190 op_sel_hi:[0,0,0]
	v_mfma_scale_f32_16x16x128_f8f6f4 v[32:35], v[8:15], v[216:223], 0, v190, v190 op_sel_hi:[0,0,0]
	s_setprio 0
	s_barrier
	s_add_i32 s48, 0, 0x18000
	s_add_i32 s49, 0, 0x1c000
	v_add_u32_e32 v12, s48, v184
	v_add_u32_e32 v28, s49, v184
	ds_read_b128 v[0:3], v12
	ds_read_b128 v[4:7], v12 offset:1024
	ds_read_b128 v[8:11], v12 offset:2048
	ds_read_b128 v[12:15], v12 offset:3072
	ds_read_b128 v[16:19], v28
	ds_read_b128 v[20:23], v28 offset:1024
	ds_read_b128 v[24:27], v28 offset:2048
	ds_read_b128 v[28:31], v28 offset:3072
	s_add_u32 s24, s24, 0x158000
	s_addc_u32 s25, s25, 0
	s_mov_b32 m0, s28
	v_lshl_add_u64 v[224:225], s[24:25], 0, v[160:161]
	ds_read_b128 v[192:195], v189 offset:32768
	ds_read_b128 v[196:199], v189 offset:33792
	ds_read_b128 v[200:203], v189 offset:34816
	ds_read_b128 v[204:207], v189 offset:35840
	ds_read_b128 v[208:211], v189 offset:36864
	ds_read_b128 v[212:215], v189 offset:37888
	ds_read_b128 v[216:219], v189 offset:38912
	ds_read_b128 v[220:223], v189 offset:39936
	global_load_lds_dwordx4 v[224:225], off
	v_lshl_add_u64 v[224:225], s[24:25], 0, v[166:167]
	s_mov_b32 m0, s29
	s_nop 0
	global_load_lds_dwordx4 v[224:225], off
	s_waitcnt vmcnt(8)
	s_waitcnt lgkmcnt(0)
	s_barrier
	s_setprio 1
	s_waitcnt lgkmcnt(0)
	v_mfma_scale_f32_16x16x128_f8f6f4 v[156:159], v[0:7], v[192:199], v[156:159], v190, v190 op_sel_hi:[0,0,0]
	v_mfma_scale_f32_16x16x128_f8f6f4 v[152:155], v[8:15], v[192:199], v[152:155], v190, v190 op_sel_hi:[0,0,0]
	v_mfma_scale_f32_16x16x128_f8f6f4 v[148:151], v[0:7], v[200:207], v[148:151], v190, v190 op_sel_hi:[0,0,0]
	v_mfma_scale_f32_16x16x128_f8f6f4 v[144:147], v[8:15], v[200:207], v[144:147], v190, v190 op_sel_hi:[0,0,0]
	v_mfma_scale_f32_16x16x128_f8f6f4 v[132:135], v[0:7], v[208:215], v[132:135], v190, v190 op_sel_hi:[0,0,0]
	v_mfma_scale_f32_16x16x128_f8f6f4 v[120:123], v[8:15], v[208:215], v[120:123], v190, v190 op_sel_hi:[0,0,0]
	v_mfma_scale_f32_16x16x128_f8f6f4 v[112:115], v[0:7], v[216:223], v[112:115], v190, v190 op_sel_hi:[0,0,0]
	v_mfma_scale_f32_16x16x128_f8f6f4 v[104:107], v[8:15], v[216:223], v[104:107], v190, v190 op_sel_hi:[0,0,0]
	s_setprio 0
	s_setprio 1
	v_mfma_scale_f32_16x16x128_f8f6f4 v[140:143], v[16:23], v[192:199], v[140:143], v190, v190 op_sel_hi:[0,0,0]
	v_mfma_scale_f32_16x16x128_f8f6f4 v[136:139], v[24:31], v[192:199], v[136:139], v190, v190 op_sel_hi:[0,0,0]
	v_mfma_scale_f32_16x16x128_f8f6f4 v[128:131], v[16:23], v[200:207], v[128:131], v190, v190 op_sel_hi:[0,0,0]
	v_mfma_scale_f32_16x16x128_f8f6f4 v[124:127], v[24:31], v[200:207], v[124:127], v190, v190 op_sel_hi:[0,0,0]
	v_mfma_scale_f32_16x16x128_f8f6f4 v[116:119], v[16:23], v[208:215], v[116:119], v190, v190 op_sel_hi:[0,0,0]
	v_mfma_scale_f32_16x16x128_f8f6f4 v[108:111], v[24:31], v[208:215], v[108:111], v190, v190 op_sel_hi:[0,0,0]
	v_mfma_scale_f32_16x16x128_f8f6f4 v[100:103], v[16:23], v[216:223], v[100:103], v190, v190 op_sel_hi:[0,0,0]
	v_mfma_scale_f32_16x16x128_f8f6f4 v[96:99], v[24:31], v[216:223], v[96:99], v190, v190 op_sel_hi:[0,0,0]
	s_setprio 0
	s_barrier
	s_add_i32 s24, s48, s15
	v_lshl_add_u64 v[176:177], v[176:177], 0, s[8:9]
	s_mov_b32 m0, s24
	ds_read_b128 v[192:195], v189 offset:49152
	ds_read_b128 v[196:199], v189 offset:50176
	ds_read_b128 v[200:203], v189 offset:51200
	ds_read_b128 v[204:207], v189 offset:52224
	ds_read_b128 v[208:211], v189 offset:53248
	ds_read_b128 v[212:215], v189 offset:54272
	ds_read_b128 v[216:219], v189 offset:55296
	ds_read_b128 v[220:223], v189 offset:56320
	global_load_lds_dwordx4 v[176:177], off
	s_add_i32 m0, s24, 0x2000
	s_add_u32 s22, s22, 0x158080
	v_lshl_add_u64 v[176:177], v[178:179], 0, s[8:9]
	s_addc_u32 s23, s23, 0
	s_add_i32 s24, s49, s15
	global_load_lds_dwordx4 v[176:177], off
	v_lshl_add_u64 v[176:177], s[22:23], 0, v[164:165]
	s_mov_b32 m0, s24
	s_nop 0
	global_load_lds_dwordx4 v[176:177], off
	v_lshl_add_u64 v[176:177], s[22:23], 0, v[168:169]
	s_add_i32 m0, s24, 0x2000
	s_nop 0
	global_load_lds_dwordx4 v[176:177], off
	v_lshl_add_u64 v[176:177], v[180:181], 0, s[8:9]
	s_mov_b32 m0, s31
	s_nop 0
	global_load_lds_dwordx4 v[176:177], off
	v_lshl_add_u64 v[176:177], v[182:183], 0, s[8:9]
	s_mov_b32 m0, s33
	s_nop 0
	global_load_lds_dwordx4 v[176:177], off
	s_waitcnt vmcnt(8)
	s_waitcnt lgkmcnt(0)
	s_barrier
	s_setprio 1
	s_waitcnt lgkmcnt(0)
	v_mfma_scale_f32_16x16x128_f8f6f4 v[92:95], v[0:7], v[192:199], v[92:95], v190, v190 op_sel_hi:[0,0,0]
	v_mfma_scale_f32_16x16x128_f8f6f4 v[88:91], v[8:15], v[192:199], v[88:91], v190, v190 op_sel_hi:[0,0,0]
	v_mfma_scale_f32_16x16x128_f8f6f4 v[80:83], v[0:7], v[200:207], v[80:83], v190, v190 op_sel_hi:[0,0,0]
	v_mfma_scale_f32_16x16x128_f8f6f4 v[72:75], v[8:15], v[200:207], v[72:75], v190, v190 op_sel_hi:[0,0,0]
	v_mfma_scale_f32_16x16x128_f8f6f4 v[64:67], v[0:7], v[208:215], v[64:67], v190, v190 op_sel_hi:[0,0,0]
	v_mfma_scale_f32_16x16x128_f8f6f4 v[56:59], v[8:15], v[208:215], v[56:59], v190, v190 op_sel_hi:[0,0,0]
	v_mfma_scale_f32_16x16x128_f8f6f4 v[48:51], v[0:7], v[216:223], v[48:51], v190, v190 op_sel_hi:[0,0,0]
	v_mfma_scale_f32_16x16x128_f8f6f4 v[40:43], v[8:15], v[216:223], v[40:43], v190, v190 op_sel_hi:[0,0,0]
	s_setprio 0
	s_setprio 1
	v_mfma_scale_f32_16x16x128_f8f6f4 v[84:87], v[16:23], v[192:199], v[84:87], v190, v190 op_sel_hi:[0,0,0]
	v_mfma_scale_f32_16x16x128_f8f6f4 v[76:79], v[24:31], v[192:199], v[76:79], v190, v190 op_sel_hi:[0,0,0]
	v_mfma_scale_f32_16x16x128_f8f6f4 v[68:71], v[16:23], v[200:207], v[68:71], v190, v190 op_sel_hi:[0,0,0]
	v_mfma_scale_f32_16x16x128_f8f6f4 v[60:63], v[24:31], v[200:207], v[60:63], v190, v190 op_sel_hi:[0,0,0]
	v_mfma_scale_f32_16x16x128_f8f6f4 v[52:55], v[16:23], v[208:215], v[52:55], v190, v190 op_sel_hi:[0,0,0]
	v_mfma_scale_f32_16x16x128_f8f6f4 v[44:47], v[24:31], v[208:215], v[44:47], v190, v190 op_sel_hi:[0,0,0]
	v_mfma_scale_f32_16x16x128_f8f6f4 v[36:39], v[16:23], v[216:223], v[36:39], v190, v190 op_sel_hi:[0,0,0]
	v_mfma_scale_f32_16x16x128_f8f6f4 v[32:35], v[24:31], v[216:223], v[32:35], v190, v190 op_sel_hi:[0,0,0]
	s_setprio 0
	s_barrier
	s_add_i32 s43, s43, 2
	s_add_u32 s20, s20, 0x100
	s_addc_u32 s21, s21, 0
	s_add_u32 s41, s41, 0x100
	s_addc_u32 s42, s42, 0
